# speedup vs baseline: 1.0108x; 1.0062x over previous
.LBB0_225:
	s_or_b64 exec, exec, s[58:59]
	s_xor_b64 s[56:57], s[56:57], -1
	s_mov_b64 s[58:59], -1
	s_and_b64 vcc, exec, s[56:57]
	s_cbranch_vccz .LBB0_227
	s_waitcnt vmcnt(22)
	s_mov_b64 s[58:59], 0

.LBB0_229:
	s_mov_b64 s[58:59], -1
	s_and_b64 vcc, exec, s[56:57]
	s_barrier
	s_cbranch_vccz .LBB0_231
	s_waitcnt vmcnt(22)
	s_mov_b64 s[58:59], 0

.LBB0_234:
	ds_read_b128 v[140:143], v138
	ds_read_b128 v[144:147], v138 offset:1024
	ds_read_b128 v[148:151], v138 offset:2048
	ds_read_b128 v[152:155], v138 offset:3072
	ds_read_b128 v[156:159], v193
	ds_read_b128 v[160:163], v193 offset:1024
	ds_read_b128 v[194:197], v192
	ds_read_b128 v[198:201], v192 offset:1024
	ds_read_b128 v[202:205], v191
	ds_read_b128 v[206:209], v191 offset:1024
	ds_read_b128 v[210:213], v190
	ds_read_b128 v[214:217], v190 offset:1024
	s_waitcnt lgkmcnt(8)
	s_waitcnt vmcnt(10)
	s_barrier
	s_waitcnt lgkmcnt(0)
	s_waitcnt lgkmcnt(0)
	v_mfma_f32_16x16x32_bf16 v[124:127], v[140:143], v[156:159], v[124:127]
	v_mfma_f32_16x16x32_bf16 v[120:123], v[148:151], v[156:159], v[120:123]
	v_mfma_f32_16x16x32_bf16 v[116:119], v[140:143], v[194:197], v[116:119]
	v_mfma_f32_16x16x32_bf16 v[112:115], v[148:151], v[194:197], v[112:115]
	v_mfma_f32_16x16x32_bf16 v[108:111], v[140:143], v[202:205], v[108:111]
	v_mfma_f32_16x16x32_bf16 v[104:107], v[148:151], v[202:205], v[104:107]
	v_mfma_f32_16x16x32_bf16 v[100:103], v[140:143], v[210:213], v[100:103]
	v_mfma_f32_16x16x32_bf16 v[96:99], v[148:151], v[210:213], v[96:99]
	v_mfma_f32_16x16x32_bf16 v[124:127], v[144:147], v[160:163], v[124:127]
	v_mfma_f32_16x16x32_bf16 v[120:123], v[152:155], v[160:163], v[120:123]
	v_mfma_f32_16x16x32_bf16 v[116:119], v[144:147], v[198:201], v[116:119]
	v_mfma_f32_16x16x32_bf16 v[112:115], v[152:155], v[198:201], v[112:115]
	v_mfma_f32_16x16x32_bf16 v[108:111], v[144:147], v[206:209], v[108:111]
	v_mfma_f32_16x16x32_bf16 v[104:107], v[152:155], v[206:209], v[104:107]
	v_mfma_f32_16x16x32_bf16 v[100:103], v[144:147], v[214:217], v[100:103]
	v_mfma_f32_16x16x32_bf16 v[96:99], v[152:155], v[214:217], v[96:99]
	s_barrier
	s_add_i32 s82, s98, 0x10000
	v_lshl_add_u64 v[234:235], s[60:61], 0, v[164:165]
	s_mov_b32 m0, s82
	s_add_i32 s82, s98, 0x12000
	ds_read_b128 v[218:221], v135
	ds_read_b128 v[222:225], v135 offset:1024
	ds_read_b128 v[226:229], v135 offset:2048
	ds_read_b128 v[230:233], v135 offset:3072
	global_load_lds_dwordx4 v[234:235], off
	v_lshl_add_u64 v[236:237], v[234:235], 0, s[2:3]
	s_mov_b32 m0, s82
	s_nop 0
	global_load_lds_dwordx4 v[236:237], off
	s_mov_b32 s82, s98
	v_lshl_add_u64 v[236:237], v[128:129], 0, s[22:23]
	s_mov_b32 m0, s82
	s_add_i32 s82, s98, 0x2000
	global_load_lds_dwordx4 v[236:237], off
	v_lshl_add_u64 v[236:237], v[128:129], 0, s[24:25]
	s_mov_b32 m0, s82
	s_nop 0
	global_load_lds_dwordx4 v[236:237], off
	s_waitcnt vmcnt(12)
	s_barrier
	s_waitcnt lgkmcnt(0)
	s_waitcnt lgkmcnt(0)
	v_mfma_f32_16x16x32_bf16 v[92:95], v[218:221], v[156:159], v[92:95]
	v_mfma_f32_16x16x32_bf16 v[88:91], v[226:229], v[156:159], v[88:91]
	v_mfma_f32_16x16x32_bf16 v[84:87], v[218:221], v[194:197], v[84:87]
	v_mfma_f32_16x16x32_bf16 v[80:83], v[226:229], v[194:197], v[80:83]
	v_mfma_f32_16x16x32_bf16 v[76:79], v[218:221], v[202:205], v[76:79]
	v_mfma_f32_16x16x32_bf16 v[72:75], v[226:229], v[202:205], v[72:75]
	v_mfma_f32_16x16x32_bf16 v[68:71], v[218:221], v[210:213], v[68:71]
	v_mfma_f32_16x16x32_bf16 v[64:67], v[226:229], v[210:213], v[64:67]
	v_mfma_f32_16x16x32_bf16 v[92:95], v[222:225], v[160:163], v[92:95]
	v_mfma_f32_16x16x32_bf16 v[88:91], v[230:233], v[160:163], v[88:91]
	v_mfma_f32_16x16x32_bf16 v[84:87], v[222:225], v[198:201], v[84:87]
	v_mfma_f32_16x16x32_bf16 v[80:83], v[230:233], v[198:201], v[80:83]
	v_mfma_f32_16x16x32_bf16 v[76:79], v[222:225], v[206:209], v[76:79]
	v_mfma_f32_16x16x32_bf16 v[72:75], v[230:233], v[206:209], v[72:75]
	v_mfma_f32_16x16x32_bf16 v[68:71], v[222:225], v[214:217], v[68:71]
	v_mfma_f32_16x16x32_bf16 v[64:67], v[230:233], v[214:217], v[64:67]
	s_barrier
	ds_read_b128 v[156:159], v193 offset:16384
	ds_read_b128 v[160:163], v193 offset:17408
	ds_read_b128 v[194:197], v192 offset:16384
	ds_read_b128 v[198:201], v192 offset:17408
	ds_read_b128 v[202:205], v191 offset:16384
	ds_read_b128 v[206:209], v191 offset:17408
	ds_read_b128 v[210:213], v190 offset:16384
	ds_read_b128 v[214:217], v190 offset:17408
	s_add_i32 s82, s98, 0x14000
	v_lshl_add_u64 v[236:237], v[234:235], 0, s[6:7]
	s_mov_b32 m0, s82
	s_add_i32 s82, s98, 0x16000
	global_load_lds_dwordx4 v[236:237], off
	v_lshl_add_u64 v[236:237], v[234:235], 0, s[8:9]
	s_mov_b32 m0, s82
	s_nop 0
	global_load_lds_dwordx4 v[236:237], off
	s_barrier
	s_waitcnt lgkmcnt(0)
	s_waitcnt lgkmcnt(0)
	v_mfma_f32_16x16x32_bf16 v[60:63], v[140:143], v[156:159], v[60:63]
	v_mfma_f32_16x16x32_bf16 v[56:59], v[148:151], v[156:159], v[56:59]
	v_mfma_f32_16x16x32_bf16 v[52:55], v[140:143], v[194:197], v[52:55]
	v_mfma_f32_16x16x32_bf16 v[48:51], v[148:151], v[194:197], v[48:51]
	v_mfma_f32_16x16x32_bf16 v[44:47], v[140:143], v[202:205], v[44:47]
	v_mfma_f32_16x16x32_bf16 v[40:43], v[148:151], v[202:205], v[40:43]
	v_mfma_f32_16x16x32_bf16 v[36:39], v[140:143], v[210:213], v[36:39]
	v_mfma_f32_16x16x32_bf16 v[32:35], v[148:151], v[210:213], v[32:35]
	v_mfma_f32_16x16x32_bf16 v[60:63], v[144:147], v[160:163], v[60:63]
	v_mfma_f32_16x16x32_bf16 v[56:59], v[152:155], v[160:163], v[56:59]
	v_mfma_f32_16x16x32_bf16 v[52:55], v[144:147], v[198:201], v[52:55]
	v_mfma_f32_16x16x32_bf16 v[48:51], v[152:155], v[198:201], v[48:51]
	v_mfma_f32_16x16x32_bf16 v[44:47], v[144:147], v[206:209], v[44:47]
	v_mfma_f32_16x16x32_bf16 v[40:43], v[152:155], v[206:209], v[40:43]
	v_mfma_f32_16x16x32_bf16 v[36:39], v[144:147], v[214:217], v[36:39]
	v_mfma_f32_16x16x32_bf16 v[32:35], v[152:155], v[214:217], v[32:35]
	s_barrier
	s_add_i32 s82, s98, 0x4000
	v_lshl_add_u64 v[142:143], v[128:129], 0, s[26:27]
	s_mov_b32 m0, s82
	s_add_i32 s82, s98, 0x6000
	global_load_lds_dwordx4 v[142:143], off
	s_mov_b32 m0, s82
	s_nop 0
	global_load_lds_dwordx4 v[128:129], off
	s_waitcnt vmcnt(12)
	s_barrier
	v_mfma_f32_16x16x32_bf16 v[28:31], v[218:221], v[156:159], v[28:31]
	v_mfma_f32_16x16x32_bf16 v[24:27], v[226:229], v[156:159], v[24:27]
	v_mfma_f32_16x16x32_bf16 v[20:23], v[218:221], v[194:197], v[20:23]
	v_mfma_f32_16x16x32_bf16 v[16:19], v[226:229], v[194:197], v[16:19]
	v_mfma_f32_16x16x32_bf16 v[12:15], v[218:221], v[202:205], v[12:15]
	v_mfma_f32_16x16x32_bf16 v[8:11], v[226:229], v[202:205], v[8:11]
	v_mfma_f32_16x16x32_bf16 v[4:7], v[218:221], v[210:213], v[4:7]
	v_mfma_f32_16x16x32_bf16 v[0:3], v[226:229], v[210:213], v[0:3]
	v_mfma_f32_16x16x32_bf16 v[28:31], v[222:225], v[160:163], v[28:31]
	v_mfma_f32_16x16x32_bf16 v[24:27], v[230:233], v[160:163], v[24:27]
	v_mfma_f32_16x16x32_bf16 v[20:23], v[222:225], v[198:201], v[20:23]
	v_mfma_f32_16x16x32_bf16 v[16:19], v[230:233], v[198:201], v[16:19]
	v_mfma_f32_16x16x32_bf16 v[12:15], v[222:225], v[206:209], v[12:15]
	v_mfma_f32_16x16x32_bf16 v[8:11], v[230:233], v[206:209], v[8:11]
	v_mfma_f32_16x16x32_bf16 v[4:7], v[222:225], v[214:217], v[4:7]
	v_mfma_f32_16x16x32_bf16 v[0:3], v[230:233], v[214:217], v[0:3]
	s_barrier
	ds_read_b128 v[140:143], v130
	ds_read_b128 v[144:147], v130 offset:1024
	ds_read_b128 v[148:151], v130 offset:2048
	ds_read_b128 v[152:155], v130 offset:3072
	ds_read_b128 v[156:159], v193 offset:32768
	ds_read_b128 v[160:163], v193 offset:33792
	ds_read_b128 v[194:197], v192 offset:32768
	ds_read_b128 v[198:201], v192 offset:33792
	ds_read_b128 v[202:205], v191 offset:32768
	ds_read_b128 v[206:209], v191 offset:33792
	ds_read_b128 v[210:213], v190 offset:32768
	ds_read_b128 v[214:217], v190 offset:33792
	s_waitcnt lgkmcnt(8)
	s_waitcnt vmcnt(10)
	s_barrier
	s_waitcnt lgkmcnt(0)
	s_waitcnt lgkmcnt(0)
	v_mfma_f32_16x16x32_bf16 v[124:127], v[140:143], v[156:159], v[124:127]
	v_mfma_f32_16x16x32_bf16 v[120:123], v[148:151], v[156:159], v[120:123]
	v_mfma_f32_16x16x32_bf16 v[116:119], v[140:143], v[194:197], v[116:119]
	v_mfma_f32_16x16x32_bf16 v[112:115], v[148:151], v[194:197], v[112:115]
	v_mfma_f32_16x16x32_bf16 v[108:111], v[140:143], v[202:205], v[108:111]
	v_mfma_f32_16x16x32_bf16 v[104:107], v[148:151], v[202:205], v[104:107]
	v_mfma_f32_16x16x32_bf16 v[100:103], v[140:143], v[210:213], v[100:103]
	v_mfma_f32_16x16x32_bf16 v[96:99], v[148:151], v[210:213], v[96:99]
	v_mfma_f32_16x16x32_bf16 v[124:127], v[144:147], v[160:163], v[124:127]
	v_mfma_f32_16x16x32_bf16 v[120:123], v[152:155], v[160:163], v[120:123]
	v_mfma_f32_16x16x32_bf16 v[116:119], v[144:147], v[198:201], v[116:119]
	v_mfma_f32_16x16x32_bf16 v[112:115], v[152:155], v[198:201], v[112:115]
	v_mfma_f32_16x16x32_bf16 v[108:111], v[144:147], v[206:209], v[108:111]
	v_mfma_f32_16x16x32_bf16 v[104:107], v[152:155], v[206:209], v[104:107]
	v_mfma_f32_16x16x32_bf16 v[100:103], v[144:147], v[214:217], v[100:103]
	v_mfma_f32_16x16x32_bf16 v[96:99], v[152:155], v[214:217], v[96:99]
	s_barrier
	s_add_i32 s82, s98, 0x18000
	v_lshl_add_u64 v[234:235], s[56:57], 0, v[164:165]
	s_mov_b32 m0, s82
	s_add_i32 s82, s98, 0x1a000
	ds_read_b128 v[218:221], v132
	ds_read_b128 v[222:225], v132 offset:1024
	ds_read_b128 v[226:229], v132 offset:2048
	ds_read_b128 v[230:233], v132 offset:3072
	global_load_lds_dwordx4 v[234:235], off
	v_lshl_add_u64 v[236:237], v[234:235], 0, s[2:3]
	s_mov_b32 m0, s82
	s_nop 0
	global_load_lds_dwordx4 v[236:237], off
	s_add_i32 s82, s98, 0x8000
	v_lshl_add_u64 v[236:237], v[128:129], 0, s[28:29]
	s_mov_b32 m0, s82
	s_add_i32 s82, s98, 0xa000
	global_load_lds_dwordx4 v[236:237], off
	v_lshl_add_u64 v[236:237], v[128:129], 0, s[30:31]
	s_mov_b32 m0, s82
	s_nop 0
	global_load_lds_dwordx4 v[236:237], off
	s_waitcnt vmcnt(12)
	s_barrier
	s_waitcnt lgkmcnt(0)
	s_waitcnt lgkmcnt(0)
	v_mfma_f32_16x16x32_bf16 v[92:95], v[218:221], v[156:159], v[92:95]
	v_mfma_f32_16x16x32_bf16 v[88:91], v[226:229], v[156:159], v[88:91]
	v_mfma_f32_16x16x32_bf16 v[84:87], v[218:221], v[194:197], v[84:87]
	v_mfma_f32_16x16x32_bf16 v[80:83], v[226:229], v[194:197], v[80:83]
	v_mfma_f32_16x16x32_bf16 v[76:79], v[218:221], v[202:205], v[76:79]
	v_mfma_f32_16x16x32_bf16 v[72:75], v[226:229], v[202:205], v[72:75]
	v_mfma_f32_16x16x32_bf16 v[68:71], v[218:221], v[210:213], v[68:71]
	v_mfma_f32_16x16x32_bf16 v[64:67], v[226:229], v[210:213], v[64:67]
	v_mfma_f32_16x16x32_bf16 v[92:95], v[222:225], v[160:163], v[92:95]
	v_mfma_f32_16x16x32_bf16 v[88:91], v[230:233], v[160:163], v[88:91]
	v_mfma_f32_16x16x32_bf16 v[84:87], v[222:225], v[198:201], v[84:87]
	v_mfma_f32_16x16x32_bf16 v[80:83], v[230:233], v[198:201], v[80:83]
	v_mfma_f32_16x16x32_bf16 v[76:79], v[222:225], v[206:209], v[76:79]
	v_mfma_f32_16x16x32_bf16 v[72:75], v[230:233], v[206:209], v[72:75]
	v_mfma_f32_16x16x32_bf16 v[68:71], v[222:225], v[214:217], v[68:71]
	v_mfma_f32_16x16x32_bf16 v[64:67], v[230:233], v[214:217], v[64:67]
	s_barrier
	ds_read_b128 v[156:159], v193 offset:49152
	ds_read_b128 v[160:163], v193 offset:50176
	ds_read_b128 v[194:197], v192 offset:49152
	ds_read_b128 v[198:201], v192 offset:50176
	ds_read_b128 v[202:205], v191 offset:49152
	ds_read_b128 v[206:209], v191 offset:50176
	ds_read_b128 v[210:213], v190 offset:49152
	ds_read_b128 v[214:217], v190 offset:50176
	s_add_i32 s82, s98, 0x1c000
	v_lshl_add_u64 v[236:237], v[234:235], 0, s[6:7]
	s_mov_b32 m0, s82
	s_add_i32 s82, s98, 0x1e000
	global_load_lds_dwordx4 v[236:237], off
	v_lshl_add_u64 v[236:237], v[234:235], 0, s[8:9]
	s_mov_b32 m0, s82
	s_nop 0
	global_load_lds_dwordx4 v[236:237], off
	s_barrier
	s_waitcnt lgkmcnt(0)
	s_waitcnt lgkmcnt(0)
	v_mfma_f32_16x16x32_bf16 v[60:63], v[140:143], v[156:159], v[60:63]
	v_mfma_f32_16x16x32_bf16 v[56:59], v[148:151], v[156:159], v[56:59]
	v_mfma_f32_16x16x32_bf16 v[52:55], v[140:143], v[194:197], v[52:55]
	v_mfma_f32_16x16x32_bf16 v[48:51], v[148:151], v[194:197], v[48:51]
	v_mfma_f32_16x16x32_bf16 v[44:47], v[140:143], v[202:205], v[44:47]
	v_mfma_f32_16x16x32_bf16 v[40:43], v[148:151], v[202:205], v[40:43]
	v_mfma_f32_16x16x32_bf16 v[36:39], v[140:143], v[210:213], v[36:39]
	v_mfma_f32_16x16x32_bf16 v[32:35], v[148:151], v[210:213], v[32:35]
	v_mfma_f32_16x16x32_bf16 v[60:63], v[144:147], v[160:163], v[60:63]
	v_mfma_f32_16x16x32_bf16 v[56:59], v[152:155], v[160:163], v[56:59]
	v_mfma_f32_16x16x32_bf16 v[52:55], v[144:147], v[198:201], v[52:55]
	v_mfma_f32_16x16x32_bf16 v[48:51], v[152:155], v[198:201], v[48:51]
	v_mfma_f32_16x16x32_bf16 v[44:47], v[144:147], v[206:209], v[44:47]
	v_mfma_f32_16x16x32_bf16 v[40:43], v[152:155], v[206:209], v[40:43]
	v_mfma_f32_16x16x32_bf16 v[36:39], v[144:147], v[214:217], v[36:39]
	v_mfma_f32_16x16x32_bf16 v[32:35], v[152:155], v[214:217], v[32:35]
	s_barrier
	v_lshl_add_u64 v[128:129], v[128:129], 0, s[34:35]
	s_add_i32 s82, s98, 0xc000
	v_lshl_add_u64 v[142:143], v[128:129], 0, s[18:19]
	s_mov_b32 m0, s82
	s_add_i32 s82, s98, 0xe000
	global_load_lds_dwordx4 v[142:143], off
	v_lshl_add_u64 v[142:143], v[128:129], 0, s[20:21]
	s_mov_b32 m0, s82
	s_nop 0
	global_load_lds_dwordx4 v[142:143], off
	s_waitcnt vmcnt(12)
	s_barrier
	v_mfma_f32_16x16x32_bf16 v[28:31], v[218:221], v[156:159], v[28:31]
	v_mfma_f32_16x16x32_bf16 v[24:27], v[226:229], v[156:159], v[24:27]
	v_mfma_f32_16x16x32_bf16 v[20:23], v[218:221], v[194:197], v[20:23]
	v_mfma_f32_16x16x32_bf16 v[16:19], v[226:229], v[194:197], v[16:19]
	v_mfma_f32_16x16x32_bf16 v[12:15], v[218:221], v[202:205], v[12:15]
	v_mfma_f32_16x16x32_bf16 v[8:11], v[226:229], v[202:205], v[8:11]
	v_mfma_f32_16x16x32_bf16 v[4:7], v[218:221], v[210:213], v[4:7]
	v_mfma_f32_16x16x32_bf16 v[0:3], v[226:229], v[210:213], v[0:3]
	v_mfma_f32_16x16x32_bf16 v[28:31], v[222:225], v[160:163], v[28:31]
	v_mfma_f32_16x16x32_bf16 v[24:27], v[230:233], v[160:163], v[24:27]
	v_mfma_f32_16x16x32_bf16 v[20:23], v[222:225], v[198:201], v[20:23]
	v_mfma_f32_16x16x32_bf16 v[16:19], v[230:233], v[198:201], v[16:19]
	v_mfma_f32_16x16x32_bf16 v[12:15], v[222:225], v[206:209], v[12:15]
	v_mfma_f32_16x16x32_bf16 v[8:11], v[230:233], v[206:209], v[8:11]
	v_mfma_f32_16x16x32_bf16 v[4:7], v[222:225], v[214:217], v[4:7]
	v_mfma_f32_16x16x32_bf16 v[0:3], v[230:233], v[214:217], v[0:3]
	s_add_i32 s14, s14, 2
	s_add_u32 s56, s56, s58
	s_addc_u32 s57, s57, s59
	s_add_u32 s60, s60, s58
	s_addc_u32 s61, s61, s59
	s_cmp_lt_u32 s14, 28
	s_barrier
	s_cbranch_scc1 .LBB0_234
	s_lshl_b32 s14, s62, 3
	s_or_b32 s82, s63, s14
	s_lshl_b32 s56, s82, 8
	v_lshlrev_b32_e32 v128, 3, v131
	v_lshlrev_b32_e32 v129, 5, v131
	s_or_b32 s14, s56, 0x80
	v_and_b32_e32 v128, 0x7fff0, v128
	v_and_b32_e32 v129, 32, v129
	s_lshl_b64 s[58:59], s[14:15], 13
	v_add_u32_e32 v129, v129, v134
	v_add_lshl_u32 v128, v133, v128, 13
	s_add_u32 s58, s40, s58
	v_lshl_add_u32 v164, v129, 1, v128
	s_addc_u32 s59, s41, s59
	v_lshl_add_u64 v[128:129], s[58:59], 0, v[164:165]
	v_readfirstlane_b32 s14, v137
	ds_read_b128 v[140:143], v138
	ds_read_b128 v[144:147], v138 offset:1024
	ds_read_b128 v[148:151], v138 offset:2048
	ds_read_b128 v[152:155], v138 offset:3072
	ds_read_b128 v[156:159], v193
	ds_read_b128 v[160:163], v193 offset:1024
	ds_read_b128 v[194:197], v192
	ds_read_b128 v[198:201], v192 offset:1024
	ds_read_b128 v[202:205], v191
	ds_read_b128 v[206:209], v191 offset:1024
	ds_read_b128 v[210:213], v190
	ds_read_b128 v[214:217], v190 offset:1024
	v_lshl_add_u64 v[138:139], v[128:129], 0, s[44:45]
	s_mov_b32 m0, s14
	v_readfirstlane_b32 s14, v136
	global_load_lds_dwordx4 v[138:139], off
	v_lshl_add_u64 v[128:129], v[128:129], 0, s[46:47]
	s_mov_b32 m0, s14
	s_mov_b32 s57, s15
	global_load_lds_dwordx4 v[128:129], off
	s_mul_i32 s99, s78, s84
	s_add_i32 s99, s99, s33
	s_cmpk_lt_u32 s99, 0x400
	s_cbranch_scc1 .Lxt5_has
	s_mov_b32 s99, 0
	s_branch .Lxt5_set
.Lxt5_has:
	v_mbcnt_lo_u32_b32 v248, -1, 0
	v_mbcnt_hi_u32_b32 v248, -1, v248
	v_add_u32_e32 v249, s64, v248
	v_bfe_i32 v252, v249, 27, 1
	v_lshlrev_b32_e32 v250, 4, v249
	v_lshrrev_b32_e32 v252, 22, v252
	v_add_u32_e32 v252, v250, v252
	v_and_b32_e32 v252, 0xfffffc00, v252
	v_sub_u32_e32 v252, v250, v252
	v_lshrrev_b32_e32 v253, 4, v252
	v_bitop3_b32 v252, v253, v252, 32 bitop3:0x6c
	v_ashrrev_i32_e32 v251, 31, v249
	v_ashrrev_i32_e32 v254, 31, v252
	v_lshrrev_b32_e32 v251, 26, v251
	v_lshrrev_b32_e32 v254, 26, v254
	v_add_u32_e32 v251, v249, v251
	v_add_u32_e32 v254, v252, v254
	v_ashrrev_i32_e32 v251, 6, v251
	v_lshrrev_b32_e32 v255, 6, v254
	v_and_b32_e32 v254, 0xc0, v254
	v_lshlrev_b32_e32 v253, 3, v251
	v_lshlrev_b32_e32 v251, 5, v251
	v_sub_u32_e32 v252, v252, v254
	v_and_b32_e32 v253, 0x7fff0, v253
	v_and_b32_e32 v251, 32, v251
	v_ashrrev_i16_sdwa v252, v167, sext(v252) dst_sel:DWORD dst_unused:UNUSED_PAD src0_sel:DWORD src1_sel:BYTE_0
	s_nop 0
	v_add_u32_sdwa v251, v251, sext(v252) dst_sel:DWORD dst_unused:UNUSED_PAD src0_sel:DWORD src1_sel:WORD_0
	s_nop 0
	v_and_b32_e32 v252, 32, v248
	v_add_lshl_u32 v248, v255, v253, 13
	v_lshl_add_u32 v248, v251, 1, v248
	v_bfe_i32 v251, v249, 6, 1
	v_and_b32_e32 v251, 0x200, v251
	v_lshrrev_b32_e32 v249, 7, v249
	v_and_b32_e32 v250, 0x3f0, v250
	v_add_lshl_u32 v249, v251, v249, 10
	v_bitop3_b32 v243, v249, v250, v252 bitop3:0xf6
	s_lshr_b32 s100, s99, 8
	s_lshl_b32 s100, s100, 11
	s_lshl_b32 s101, s99, 8
	s_and_b32 s101, s101, 0x700
	s_or_b32 s100, s100, s101
	s_lshl_b32 s100, s100, 13
	s_add_u32 s100, s40, s100
	s_addc_u32 s101, s41, 0
	v_mov_b32_e32 v249, 0
	v_lshl_add_u64 v[244:245], s[100:101], 0, v[248:249]
	s_and_b32 s100, s99, 0xf8
	s_lshl_b32 s100, s100, 11
	s_add_u32 s100, s65, s100
	s_addc_u32 s101, s66, 0
	v_mov_b32_e32 v252, v243
	v_mov_b32_e32 v253, 0
	v_lshl_add_u64 v[246:247], s[100:101], 0, v[252:253]
	s_mov_b32 s99, 1
.Lxt5_set:
	s_waitcnt vmcnt(10)
	s_barrier
	s_waitcnt lgkmcnt(0)
	s_setprio 1
	s_waitcnt lgkmcnt(0)
	v_mfma_f32_16x16x32_bf16 v[124:127], v[140:143], v[156:159], v[124:127]
	v_mfma_f32_16x16x32_bf16 v[120:123], v[148:151], v[156:159], v[120:123]
	v_mfma_f32_16x16x32_bf16 v[116:119], v[140:143], v[194:197], v[116:119]
	v_mfma_f32_16x16x32_bf16 v[112:115], v[148:151], v[194:197], v[112:115]
	v_mfma_f32_16x16x32_bf16 v[108:111], v[140:143], v[202:205], v[108:111]
	v_mfma_f32_16x16x32_bf16 v[104:107], v[148:151], v[202:205], v[104:107]
	v_mfma_f32_16x16x32_bf16 v[100:103], v[140:143], v[210:213], v[100:103]
	v_mfma_f32_16x16x32_bf16 v[96:99], v[148:151], v[210:213], v[96:99]
	v_mfma_f32_16x16x32_bf16 v[124:127], v[144:147], v[160:163], v[124:127]
	v_mfma_f32_16x16x32_bf16 v[120:123], v[152:155], v[160:163], v[120:123]
	v_mfma_f32_16x16x32_bf16 v[116:119], v[144:147], v[198:201], v[116:119]
	v_mfma_f32_16x16x32_bf16 v[112:115], v[152:155], v[198:201], v[112:115]
	v_mfma_f32_16x16x32_bf16 v[108:111], v[144:147], v[206:209], v[108:111]
	v_mfma_f32_16x16x32_bf16 v[104:107], v[152:155], v[206:209], v[104:107]
	v_mfma_f32_16x16x32_bf16 v[100:103], v[144:147], v[214:217], v[100:103]
	v_mfma_f32_16x16x32_bf16 v[96:99], v[152:155], v[214:217], v[96:99]
	s_setprio 0
	s_barrier
	ds_read_b128 v[136:139], v135
	ds_read_b128 v[218:221], v135 offset:1024
	ds_read_b128 v[222:225], v135 offset:2048
	ds_read_b128 v[226:229], v135 offset:3072
	s_cmp_eq_u32 s99, 0
	s_cbranch_scc1 .Lxt5_s1
	s_add_i32 m0, s98, 0x10000
	s_nop 0
	global_load_lds_dwordx4 v[246:247], off
	s_mov_b64 s[100:101], 0x1000
	s_add_i32 m0, s98, 0x12000
	v_lshl_add_u64 v[250:251], v[246:247], 0, s[100:101]
	global_load_lds_dwordx4 v[250:251], off
	s_mov_b32 m0, s98
	s_nop 0
	global_load_lds_dwordx4 v[244:245], off
	s_mov_b64 s[100:101], 0x80000
	s_add_i32 m0, s98, 0x2000
	v_lshl_add_u64 v[250:251], v[244:245], 0, s[100:101]
	global_load_lds_dwordx4 v[250:251], off
.Lxt5_s1:
	s_barrier
	s_waitcnt lgkmcnt(0)
	s_setprio 1
	s_waitcnt lgkmcnt(0)
	v_mfma_f32_16x16x32_bf16 v[92:95], v[136:139], v[156:159], v[92:95]
	v_mfma_f32_16x16x32_bf16 v[84:87], v[136:139], v[194:197], v[84:87]
	v_mfma_f32_16x16x32_bf16 v[80:83], v[222:225], v[194:197], v[80:83]
	v_mfma_f32_16x16x32_bf16 v[88:91], v[222:225], v[156:159], v[88:91]
	v_mfma_f32_16x16x32_bf16 v[76:79], v[136:139], v[202:205], v[76:79]
	v_mfma_f32_16x16x32_bf16 v[72:75], v[222:225], v[202:205], v[72:75]
	v_mfma_f32_16x16x32_bf16 v[68:71], v[136:139], v[210:213], v[68:71]
	v_mfma_f32_16x16x32_bf16 v[64:67], v[222:225], v[210:213], v[64:67]
	v_mfma_f32_16x16x32_bf16 v[156:159], v[218:221], v[160:163], v[92:95]
	v_mfma_f32_16x16x32_bf16 v[194:197], v[218:221], v[198:201], v[84:87]
	v_mfma_f32_16x16x32_bf16 v[198:201], v[226:229], v[198:201], v[80:83]
	v_mfma_f32_16x16x32_bf16 v[160:163], v[226:229], v[160:163], v[88:91]
	v_mfma_f32_16x16x32_bf16 v[202:205], v[218:221], v[206:209], v[76:79]
	v_mfma_f32_16x16x32_bf16 v[206:209], v[226:229], v[206:209], v[72:75]
	v_mfma_f32_16x16x32_bf16 v[210:213], v[218:221], v[214:217], v[68:71]
	v_mfma_f32_16x16x32_bf16 v[214:217], v[226:229], v[214:217], v[64:67]
	s_setprio 0
	s_barrier
	s_nop 0
	ds_read_b128 v[64:67], v193 offset:16384
	ds_read_b128 v[68:71], v193 offset:17408
	ds_read_b128 v[72:75], v192 offset:16384
	ds_read_b128 v[76:79], v192 offset:17408
	ds_read_b128 v[80:83], v191 offset:16384
	ds_read_b128 v[84:87], v191 offset:17408
	ds_read_b128 v[88:91], v190 offset:16384
	ds_read_b128 v[92:95], v190 offset:17408
	s_cmp_eq_u32 s99, 0
	s_cbranch_scc1 .Lxt5_s2
	s_mov_b64 s[100:101], 0x2000
	s_add_i32 m0, s98, 0x14000
	v_lshl_add_u64 v[250:251], v[246:247], 0, s[100:101]
	global_load_lds_dwordx4 v[250:251], off
	s_mov_b64 s[100:101], 0x3000
	s_add_i32 m0, s98, 0x16000
	v_lshl_add_u64 v[250:251], v[246:247], 0, s[100:101]
	global_load_lds_dwordx4 v[250:251], off
.Lxt5_s2:
	s_cmp_lg_u32 s99, 0
	s_cbranch_scc1 .Lxt5_w1l
	s_waitcnt vmcnt(4)
	s_branch .Lxt5_w1d

.Lxt5_w1d:
	s_barrier
	s_waitcnt lgkmcnt(0)
	s_setprio 1
	s_waitcnt lgkmcnt(0)
	v_mfma_f32_16x16x32_bf16 v[60:63], v[140:143], v[64:67], v[60:63]
	v_mfma_f32_16x16x32_bf16 v[56:59], v[148:151], v[64:67], v[56:59]
	v_mfma_f32_16x16x32_bf16 v[52:55], v[140:143], v[72:75], v[52:55]
	v_mfma_f32_16x16x32_bf16 v[48:51], v[148:151], v[72:75], v[48:51]
	v_mfma_f32_16x16x32_bf16 v[230:233], v[140:143], v[80:83], v[44:47]
	v_mfma_f32_16x16x32_bf16 v[234:237], v[148:151], v[80:83], v[40:43]
	v_mfma_f32_16x16x32_bf16 v[140:143], v[140:143], v[88:91], v[36:39]
	v_mfma_f32_16x16x32_bf16 v[148:151], v[148:151], v[88:91], v[32:35]
	v_mfma_f32_16x16x32_bf16 v[32:35], v[144:147], v[68:71], v[60:63]
	v_mfma_f32_16x16x32_bf16 v[36:39], v[152:155], v[68:71], v[56:59]
	v_mfma_f32_16x16x32_bf16 v[40:43], v[144:147], v[76:79], v[52:55]
	v_mfma_f32_16x16x32_bf16 v[44:47], v[152:155], v[76:79], v[48:51]
	v_mfma_f32_16x16x32_bf16 v[48:51], v[144:147], v[84:87], v[230:233]
	v_mfma_f32_16x16x32_bf16 v[52:55], v[152:155], v[84:87], v[234:237]
	v_mfma_f32_16x16x32_bf16 v[56:59], v[144:147], v[92:95], v[140:143]
	v_mfma_f32_16x16x32_bf16 v[60:63], v[152:155], v[92:95], v[148:151]
	s_setprio 0
	s_setprio 1
	v_mfma_f32_16x16x32_bf16 v[28:31], v[136:139], v[64:67], v[28:31]
	v_mfma_f32_16x16x32_bf16 v[24:27], v[222:225], v[64:67], v[24:27]
	v_mfma_f32_16x16x32_bf16 v[20:23], v[136:139], v[72:75], v[20:23]
	v_mfma_f32_16x16x32_bf16 v[64:67], v[222:225], v[72:75], v[16:19]
	v_mfma_f32_16x16x32_bf16 v[12:15], v[136:139], v[80:83], v[12:15]
	v_mfma_f32_16x16x32_bf16 v[8:11], v[222:225], v[80:83], v[8:11]
	v_mfma_f32_16x16x32_bf16 v[72:75], v[136:139], v[88:91], v[4:7]
	v_mfma_f32_16x16x32_bf16 v[80:83], v[222:225], v[88:91], v[0:3]
	v_mfma_f32_16x16x32_bf16 v[0:3], v[218:221], v[68:71], v[28:31]
	v_mfma_f32_16x16x32_bf16 v[4:7], v[226:229], v[68:71], v[24:27]
	v_mfma_f32_16x16x32_bf16 v[16:19], v[218:221], v[76:79], v[20:23]
	v_mfma_f32_16x16x32_bf16 v[20:23], v[226:229], v[76:79], v[64:67]
	v_mfma_f32_16x16x32_bf16 v[24:27], v[218:221], v[84:87], v[12:15]
	v_mfma_f32_16x16x32_bf16 v[28:31], v[226:229], v[84:87], v[8:11]
	v_mfma_f32_16x16x32_bf16 v[64:67], v[218:221], v[92:95], v[72:75]
	v_mfma_f32_16x16x32_bf16 v[68:71], v[226:229], v[92:95], v[80:83]
	s_setprio 0
	s_barrier
	ds_read_b128 v[12:15], v130
	ds_read_b128 v[8:11], v130 offset:1024
	ds_read_b128 v[76:79], v130 offset:2048
	ds_read_b128 v[72:75], v130 offset:3072
	ds_read_b128 v[140:143], v193 offset:32768
	ds_read_b128 v[148:151], v193 offset:33792
	ds_read_b128 v[218:221], v192 offset:32768
	ds_read_b128 v[222:225], v192 offset:33792
	ds_read_b128 v[226:229], v191 offset:32768
	ds_read_b128 v[230:233], v191 offset:33792
	ds_read_b128 v[234:237], v190 offset:32768
	ds_read_b128 v[238:241], v190 offset:33792
	s_cmp_eq_u32 s99, 0
	s_cbranch_scc1 .Lxt5_s3
	s_mov_b64 s[100:101], 0x100000
	s_add_i32 m0, s98, 0x4000
	v_lshl_add_u64 v[250:251], v[244:245], 0, s[100:101]
	global_load_lds_dwordx4 v[250:251], off
	s_mov_b64 s[100:101], 0x180000
	s_add_i32 m0, s98, 0x6000
	v_lshl_add_u64 v[250:251], v[244:245], 0, s[100:101]
	global_load_lds_dwordx4 v[250:251], off
.Lxt5_s3:
	s_cmp_lg_u32 s99, 0
	s_cbranch_scc1 .Lxt5_w2l
	s_waitcnt vmcnt(2)
	s_branch .Lxt5_w2d

.Lxt5_w2d:
	s_barrier
	s_waitcnt lgkmcnt(0)
	s_setprio 1
	s_waitcnt lgkmcnt(0)
	v_mfma_f32_16x16x32_bf16 v[80:83], v[12:15], v[140:143], v[124:127]
	v_mfma_f32_16x16x32_bf16 v[84:87], v[76:79], v[140:143], v[120:123]
	v_mfma_f32_16x16x32_bf16 v[88:91], v[12:15], v[218:221], v[116:119]
	v_mfma_f32_16x16x32_bf16 v[92:95], v[76:79], v[218:221], v[112:115]
	v_mfma_f32_16x16x32_bf16 v[108:111], v[12:15], v[226:229], v[108:111]
	v_mfma_f32_16x16x32_bf16 v[104:107], v[76:79], v[226:229], v[104:107]
	v_mfma_f32_16x16x32_bf16 v[100:103], v[12:15], v[234:237], v[100:103]
	v_mfma_f32_16x16x32_bf16 v[96:99], v[76:79], v[234:237], v[96:99]
	v_mfma_f32_16x16x32_bf16 v[152:155], v[8:11], v[148:151], v[80:83]
	v_mfma_f32_16x16x32_bf16 v[144:147], v[72:75], v[148:151], v[84:87]
	v_mfma_f32_16x16x32_bf16 v[136:139], v[8:11], v[222:225], v[88:91]
	v_mfma_f32_16x16x32_bf16 v[128:131], v[72:75], v[222:225], v[92:95]
	v_mfma_f32_16x16x32_bf16 v[120:123], v[8:11], v[230:233], v[108:111]
	v_mfma_f32_16x16x32_bf16 v[112:115], v[72:75], v[230:233], v[104:107]
	v_mfma_f32_16x16x32_bf16 v[104:107], v[8:11], v[238:241], v[100:103]
	v_mfma_f32_16x16x32_bf16 v[96:99], v[72:75], v[238:241], v[96:99]
	s_setprio 0
	s_barrier
	ds_read_b128 v[88:91], v132
	ds_read_b128 v[80:83], v132 offset:1024
	ds_read_b128 v[92:95], v132 offset:2048
	ds_read_b128 v[84:87], v132 offset:3072
	s_cmp_lg_u32 s99, 0
	s_cbranch_scc1 .Lxt5_w3l
	s_waitcnt vmcnt(0)
	s_branch .Lxt5_w3d
.Lxt5_w3l:
	s_waitcnt vmcnt(8)
.Lxt5_w3d:
	s_barrier
	s_waitcnt lgkmcnt(0)
	s_setprio 1
	s_waitcnt lgkmcnt(0)
	v_mfma_f32_16x16x32_bf16 v[100:103], v[88:91], v[140:143], v[156:159]
	v_mfma_f32_16x16x32_bf16 v[108:111], v[92:95], v[140:143], v[160:163]
	v_mfma_f32_16x16x32_bf16 v[116:119], v[88:91], v[218:221], v[194:197]
	v_mfma_f32_16x16x32_bf16 v[124:127], v[92:95], v[218:221], v[198:201]
	v_mfma_f32_16x16x32_bf16 v[160:163], v[88:91], v[226:229], v[202:205]
	v_mfma_f32_16x16x32_bf16 v[194:197], v[92:95], v[226:229], v[206:209]
	v_mfma_f32_16x16x32_bf16 v[198:201], v[88:91], v[234:237], v[210:213]
	v_mfma_f32_16x16x32_bf16 v[202:205], v[92:95], v[234:237], v[214:217]
	v_mfma_f32_16x16x32_bf16 v[156:159], v[80:83], v[148:151], v[100:103]
	v_mfma_f32_16x16x32_bf16 v[148:151], v[84:87], v[148:151], v[108:111]
	v_mfma_f32_16x16x32_bf16 v[140:143], v[80:83], v[222:225], v[116:119]
	v_mfma_f32_16x16x32_bf16 v[132:135], v[84:87], v[222:225], v[124:127]
	v_mfma_f32_16x16x32_bf16 v[124:127], v[80:83], v[230:233], v[160:163]
	v_mfma_f32_16x16x32_bf16 v[116:119], v[84:87], v[230:233], v[194:197]
	v_mfma_f32_16x16x32_bf16 v[108:111], v[80:83], v[238:241], v[198:201]
	v_mfma_f32_16x16x32_bf16 v[100:103], v[84:87], v[238:241], v[202:205]
	s_setprio 0
	s_lshl_b64 s[58:59], s[56:57], 2
	s_barrier
	v_mbcnt_lo_u32_b32 v162, -1, 0
	v_mbcnt_hi_u32_b32 v162, -1, v162
	s_add_u32 s58, s87, s58
	v_add_u32_e32 v160, s64, v162
	s_addc_u32 s59, s88, s59
	v_and_b32_e32 v164, 0x100, v160
	v_and_b32_e32 v162, 15, v162
	v_lshl_add_u64 v[160:161], s[58:59], 0, v[164:165]
	v_lshlrev_b32_e32 v164, 2, v162
	v_lshl_add_u64 v[160:161], v[160:161], 0, v[164:165]
	global_load_dword v180, v[160:161], off
	global_load_dword v178, v[160:161], off offset:64
	global_load_dword v176, v[160:161], off offset:128
	global_load_dword v174, v[160:161], off offset:192
	global_load_dword v172, v[160:161], off offset:512
	global_load_dword v170, v[160:161], off offset:576
	global_load_dword v168, v[160:161], off offset:640
	global_load_dword v166, v[160:161], off offset:704
	v_mbcnt_lo_u32_b32 v194, -1, 0
	v_mbcnt_hi_u32_b32 v194, -1, v194
	s_cmp_lg_u32 s81, 0
	v_add_u32_e32 v160, s64, v194
	v_bfe_u32 v196, v160, 8, 1
	v_ashrrev_i32_e32 v199, 6, v160
	v_bfe_u32 v160, v194, 4, 2
	s_cselect_b64 s[58:59], -1, 0
	v_and_b32_e32 v197, 3, v199
	v_and_b32_e32 v195, 15, v194
	s_and_b64 vcc, exec, s[58:59]
	v_lshlrev_b32_e32 v198, 4, v160
	s_cbranch_vccz .LBB0_246
	s_lshl_b32 s14, s80, 22
	s_lshl_b32 s57, s82, 14
	s_add_i32 s57, s57, s14
	v_lshlrev_b32_e32 v160, 6, v195
	v_or3_b32 v160, s57, v160, v198
	v_lshl_add_u32 v160, v197, 20, v160
	v_lshl_or_b32 v164, v196, 12, v160
	s_waitcnt vmcnt(0)
	s_cmp_eq_u32 s99, 0
	s_cbranch_scc1 .Lxt5_s4
	s_mov_b64 s[100:101], 0x100000
	s_add_i32 m0, s98, 0x18000
	v_lshl_add_u64 v[250:251], v[246:247], 0, s[100:101]
	global_load_lds_dwordx4 v[250:251], off
	s_mov_b64 s[100:101], 0x101000
	s_add_i32 m0, s98, 0x1a000
	v_lshl_add_u64 v[250:251], v[246:247], 0, s[100:101]
	global_load_lds_dwordx4 v[250:251], off
	s_mov_b64 s[100:101], 0x80
	s_add_i32 m0, s98, 0x8000
	v_lshl_add_u64 v[250:251], v[244:245], 0, s[100:101]
	global_load_lds_dwordx4 v[250:251], off
	s_mov_b64 s[100:101], 0x80080
	s_add_i32 m0, s98, 0xa000
	v_lshl_add_u64 v[250:251], v[244:245], 0, s[100:101]
	global_load_lds_dwordx4 v[250:251], off
	s_mov_b64 s[100:101], 0x102000
	s_add_i32 m0, s98, 0x1c000
	v_lshl_add_u64 v[250:251], v[246:247], 0, s[100:101]
	global_load_lds_dwordx4 v[250:251], off
	s_mov_b64 s[100:101], 0x103000
	s_add_i32 m0, s98, 0x1e000
	v_lshl_add_u64 v[250:251], v[246:247], 0, s[100:101]
	global_load_lds_dwordx4 v[250:251], off
.Lxt5_s4:
	v_pk_mul_f32 v[160:161], v[154:155], v[180:181] op_sel_hi:[1,0]
	v_pk_mul_f32 v[200:201], v[146:147], v[180:181] op_sel_hi:[1,0]
	v_max_f32_e32 v160, 0, v160
	v_mul_f32_e32 v204, v160, v160
	v_max_f32_e32 v160, 0, v200
	v_pk_mul_f32 v[162:163], v[152:153], v[180:181] op_sel_hi:[1,0]
	v_mul_f32_e32 v200, v160, v160
	v_max_f32_e32 v160, 0, v161
	v_pk_mul_f32 v[202:203], v[144:145], v[180:181] op_sel_hi:[1,0]
	v_max_f32_e32 v162, 0, v162
	v_max_f32_e32 v163, 0, v163
	v_mul_f32_e32 v161, v160, v160
	v_max_f32_e32 v160, 0, v201
	v_mul_f32_e32 v162, v162, v162
	v_max_f32_e32 v202, 0, v202
	v_mul_f32_e32 v163, v163, v163
	v_max_f32_e32 v203, 0, v203
	v_mul_f32_e32 v201, v160, v160
	v_cvt_pk_bf16_f32 v160, v162, v163
	v_cvt_pk_bf16_f32 v161, v204, v161
	v_mul_f32_e32 v202, v202, v202
	v_mul_f32_e32 v203, v203, v203
	v_cvt_pk_bf16_f32 v162, v202, v203
	v_cvt_pk_bf16_f32 v163, v200, v201
	global_store_dwordx4 v164, v[160:163], s[0:1]
	v_pk_mul_f32 v[202:203], v[150:151], v[180:181] op_sel_hi:[1,0]
	v_lshl_add_u64 v[200:201], s[0:1], 0, v[164:165]
	v_pk_mul_f32 v[160:161], v[158:159], v[180:181] op_sel_hi:[1,0]
	v_pk_mul_f32 v[162:163], v[156:157], v[180:181] op_sel_hi:[1,0]
	v_max_f32_e32 v160, 0, v160
	v_mul_f32_e32 v206, v160, v160
	v_max_f32_e32 v160, 0, v202
	v_mul_f32_e32 v202, v160, v160
	v_max_f32_e32 v160, 0, v161
	v_pk_mul_f32 v[204:205], v[148:149], v[180:181] op_sel_hi:[1,0]
	v_max_f32_e32 v162, 0, v162
	v_max_f32_e32 v163, 0, v163
	v_mul_f32_e32 v161, v160, v160
	v_max_f32_e32 v160, 0, v203
	v_add_co_u32_e32 v200, vcc, s74, v200
	v_mul_f32_e32 v162, v162, v162
	v_max_f32_e32 v204, 0, v204
	v_mul_f32_e32 v163, v163, v163
	v_max_f32_e32 v205, 0, v205
	v_mul_f32_e32 v203, v160, v160
	v_cvt_pk_bf16_f32 v160, v162, v163
	v_cvt_pk_bf16_f32 v161, v206, v161
	v_addc_co_u32_e32 v201, vcc, 0, v201, vcc
	v_mul_f32_e32 v204, v204, v204
	v_mul_f32_e32 v205, v205, v205
	v_cvt_pk_bf16_f32 v162, v204, v205
	v_cvt_pk_bf16_f32 v163, v202, v203
	global_store_dwordx4 v[200:201], v[160:163], off
	v_pk_mul_f32 v[202:203], v[130:131], v[178:179] op_sel_hi:[1,0]
	v_pk_mul_f32 v[204:205], v[128:129], v[178:179] op_sel_hi:[1,0]
	v_pk_mul_f32 v[160:161], v[138:139], v[178:179] op_sel_hi:[1,0]
	v_pk_mul_f32 v[162:163], v[136:137], v[178:179] op_sel_hi:[1,0]
	v_max_f32_e32 v160, 0, v160
	v_mul_f32_e32 v206, v160, v160
	v_max_f32_e32 v160, 0, v202
	v_mul_f32_e32 v202, v160, v160
	v_max_f32_e32 v160, 0, v161
	v_max_f32_e32 v162, 0, v162
	v_max_f32_e32 v163, 0, v163
	v_mul_f32_e32 v161, v160, v160
	v_max_f32_e32 v160, 0, v203
	v_mul_f32_e32 v162, v162, v162
	v_max_f32_e32 v204, 0, v204
	v_mul_f32_e32 v163, v163, v163
	v_max_f32_e32 v205, 0, v205
	v_mul_f32_e32 v203, v160, v160
	v_cvt_pk_bf16_f32 v160, v162, v163
	v_cvt_pk_bf16_f32 v161, v206, v161
	v_mul_f32_e32 v204, v204, v204
	v_mul_f32_e32 v205, v205, v205
	v_cvt_pk_bf16_f32 v162, v204, v205
	v_cvt_pk_bf16_f32 v163, v202, v203
	global_store_dwordx4 v164, v[160:163], s[0:1] offset:1024
	v_pk_mul_f32 v[202:203], v[134:135], v[178:179] op_sel_hi:[1,0]
	v_pk_mul_f32 v[204:205], v[132:133], v[178:179] op_sel_hi:[1,0]
	v_pk_mul_f32 v[160:161], v[142:143], v[178:179] op_sel_hi:[1,0]
	v_pk_mul_f32 v[162:163], v[140:141], v[178:179] op_sel_hi:[1,0]
	v_max_f32_e32 v160, 0, v160
	v_mul_f32_e32 v206, v160, v160
	v_max_f32_e32 v160, 0, v202
	v_mul_f32_e32 v202, v160, v160
	v_max_f32_e32 v160, 0, v161
	v_max_f32_e32 v162, 0, v162
	v_max_f32_e32 v163, 0, v163
	v_mul_f32_e32 v161, v160, v160
	v_max_f32_e32 v160, 0, v203
	v_mul_f32_e32 v162, v162, v162
	v_max_f32_e32 v204, 0, v204
	v_mul_f32_e32 v163, v163, v163
	v_max_f32_e32 v205, 0, v205
	v_mul_f32_e32 v203, v160, v160
	v_cvt_pk_bf16_f32 v160, v162, v163
	v_cvt_pk_bf16_f32 v161, v206, v161
	v_mul_f32_e32 v204, v204, v204
	v_mul_f32_e32 v205, v205, v205
	v_cvt_pk_bf16_f32 v162, v204, v205
	v_cvt_pk_bf16_f32 v163, v202, v203
	global_store_dwordx4 v[200:201], v[160:163], off offset:1024
	v_pk_mul_f32 v[202:203], v[114:115], v[176:177] op_sel_hi:[1,0]
	v_pk_mul_f32 v[204:205], v[112:113], v[176:177] op_sel_hi:[1,0]
	v_pk_mul_f32 v[160:161], v[122:123], v[176:177] op_sel_hi:[1,0]
	v_pk_mul_f32 v[162:163], v[120:121], v[176:177] op_sel_hi:[1,0]
	v_max_f32_e32 v160, 0, v160
	v_mul_f32_e32 v206, v160, v160
	v_max_f32_e32 v160, 0, v202
	v_mul_f32_e32 v202, v160, v160
	v_max_f32_e32 v160, 0, v161
	v_max_f32_e32 v162, 0, v162
	v_max_f32_e32 v163, 0, v163
	v_mul_f32_e32 v161, v160, v160
	v_max_f32_e32 v160, 0, v203
	v_mul_f32_e32 v162, v162, v162
	v_max_f32_e32 v204, 0, v204
	v_mul_f32_e32 v163, v163, v163
	v_max_f32_e32 v205, 0, v205
	v_mul_f32_e32 v203, v160, v160
	v_cvt_pk_bf16_f32 v160, v162, v163
	v_cvt_pk_bf16_f32 v161, v206, v161
	v_mul_f32_e32 v204, v204, v204
	v_mul_f32_e32 v205, v205, v205
	v_cvt_pk_bf16_f32 v162, v204, v205
	v_cvt_pk_bf16_f32 v163, v202, v203
	global_store_dwordx4 v164, v[160:163], s[0:1] offset:2048
	v_pk_mul_f32 v[202:203], v[118:119], v[176:177] op_sel_hi:[1,0]
	v_pk_mul_f32 v[204:205], v[116:117], v[176:177] op_sel_hi:[1,0]
	v_pk_mul_f32 v[160:161], v[126:127], v[176:177] op_sel_hi:[1,0]
	v_pk_mul_f32 v[162:163], v[124:125], v[176:177] op_sel_hi:[1,0]
	v_max_f32_e32 v160, 0, v160
	v_mul_f32_e32 v206, v160, v160
	v_max_f32_e32 v160, 0, v202
	v_mul_f32_e32 v202, v160, v160
	v_max_f32_e32 v160, 0, v161
	v_max_f32_e32 v162, 0, v162
	v_max_f32_e32 v163, 0, v163
	v_mul_f32_e32 v161, v160, v160
	v_max_f32_e32 v160, 0, v203
	v_mul_f32_e32 v162, v162, v162
	v_max_f32_e32 v204, 0, v204
	v_mul_f32_e32 v163, v163, v163
	v_max_f32_e32 v205, 0, v205
	v_mul_f32_e32 v203, v160, v160
	v_cvt_pk_bf16_f32 v160, v162, v163
	v_cvt_pk_bf16_f32 v161, v206, v161
	v_mul_f32_e32 v204, v204, v204
	v_mul_f32_e32 v205, v205, v205
	v_cvt_pk_bf16_f32 v162, v204, v205
	v_cvt_pk_bf16_f32 v163, v202, v203
	global_store_dwordx4 v[200:201], v[160:163], off offset:2048
	v_pk_mul_f32 v[200:201], v[98:99], v[174:175] op_sel_hi:[1,0]
	v_pk_mul_f32 v[202:203], v[96:97], v[174:175] op_sel_hi:[1,0]
	v_pk_mul_f32 v[160:161], v[106:107], v[174:175] op_sel_hi:[1,0]
	v_pk_mul_f32 v[162:163], v[104:105], v[174:175] op_sel_hi:[1,0]
	v_max_f32_e32 v160, 0, v160
	v_mul_f32_e32 v204, v160, v160
	v_max_f32_e32 v160, 0, v200
	v_mul_f32_e32 v200, v160, v160
	v_max_f32_e32 v160, 0, v161
	v_max_f32_e32 v162, 0, v162
	v_max_f32_e32 v163, 0, v163
	v_mul_f32_e32 v161, v160, v160
	v_max_f32_e32 v160, 0, v201
	v_mul_f32_e32 v162, v162, v162
	v_max_f32_e32 v202, 0, v202
	v_mul_f32_e32 v163, v163, v163
	v_max_f32_e32 v203, 0, v203
	v_mul_f32_e32 v201, v160, v160
	v_cvt_pk_bf16_f32 v160, v162, v163
	v_cvt_pk_bf16_f32 v161, v204, v161
	v_mul_f32_e32 v202, v202, v202
	v_mul_f32_e32 v203, v203, v203
	v_cvt_pk_bf16_f32 v162, v202, v203
	v_cvt_pk_bf16_f32 v163, v200, v201
	global_store_dwordx4 v164, v[160:163], s[0:1] offset:3072
	v_pk_mul_f32 v[200:201], v[102:103], v[174:175] op_sel_hi:[1,0]
	v_pk_mul_f32 v[202:203], v[100:101], v[174:175] op_sel_hi:[1,0]
	v_pk_mul_f32 v[160:161], v[110:111], v[174:175] op_sel_hi:[1,0]
	v_pk_mul_f32 v[162:163], v[108:109], v[174:175] op_sel_hi:[1,0]
	v_max_f32_e32 v160, 0, v160
	v_mul_f32_e32 v204, v160, v160
	v_max_f32_e32 v160, 0, v200
	v_max_f32_e32 v162, 0, v162
	v_max_f32_e32 v163, 0, v163
	v_mul_f32_e32 v200, v160, v160
	v_max_f32_e32 v160, 0, v161
	v_mul_f32_e32 v162, v162, v162
	v_max_f32_e32 v202, 0, v202
	v_mul_f32_e32 v163, v163, v163
	v_max_f32_e32 v203, 0, v203
	v_mul_f32_e32 v161, v160, v160
	v_max_f32_e32 v160, 0, v201
	v_mul_f32_e32 v202, v202, v202
	v_mul_f32_e32 v203, v203, v203
	v_mul_f32_e32 v201, v160, v160
	v_cvt_pk_bf16_f32 v160, v162, v163
	v_cvt_pk_bf16_f32 v161, v204, v161
	v_cvt_pk_bf16_f32 v162, v202, v203
	v_cvt_pk_bf16_f32 v163, v200, v201
	v_add_u32_e32 v164, 0x80c00, v164
	s_cbranch_execnz .LBB0_238

.LBB0_243:
	v_mbcnt_lo_u32_b32 v64, -1, 0
	v_mbcnt_hi_u32_b32 v64, -1, v64
	s_lshl_b32 s57, s83, 3
	v_add_u32_e32 v65, s64, v64
	v_bfe_i32 v68, v65, 27, 1
	v_lshlrev_b32_e32 v66, 4, v65
	v_lshrrev_b32_e32 v68, 22, v68
	v_add_u32_e32 v68, v66, v68
	v_and_b32_e32 v68, 0xfffffc00, v68
	v_sub_u32_e32 v68, v66, v68
	v_lshrrev_b32_e32 v69, 4, v68
	v_bitop3_b32 v68, v69, v68, 32 bitop3:0x6c
	v_ashrrev_i32_e32 v67, 31, v65
	v_ashrrev_i32_e32 v70, 31, v68
	v_lshrrev_b32_e32 v67, 26, v67
	v_lshrrev_b32_e32 v70, 26, v70
	v_add_u32_e32 v67, v65, v67
	v_add_u32_e32 v70, v68, v70
	v_ashrrev_i32_e32 v67, 6, v67
	v_lshrrev_b32_e32 v71, 6, v70
	v_and_b32_e32 v70, 0xc0, v70
	v_lshlrev_b32_e32 v69, 3, v67
	v_lshlrev_b32_e32 v67, 5, v67
	v_sub_u32_e32 v68, v68, v70
	s_ff1_i32_b32 s62, s57
	s_add_i32 s57, s57, -1
	v_and_b32_e32 v69, 0x7fff0, v69
	v_and_b32_e32 v67, 32, v67
	v_ashrrev_i16_sdwa v68, v167, sext(v68) dst_sel:DWORD dst_unused:UNUSED_PAD src0_sel:DWORD src1_sel:BYTE_0
	s_lshr_b32 s62, s85, s62
	s_and_b32 s57, s57, s85
	s_lshl_b32 s63, s85, 8
	v_add_u32_sdwa v67, v67, sext(v68) dst_sel:DWORD dst_unused:UNUSED_PAD src0_sel:DWORD src1_sel:WORD_0
	v_and_b32_e32 v68, 32, v64
	v_add_lshl_u32 v64, v71, v69, 13
	s_lshl_b32 s62, s62, 11
	s_and_b32 s63, s63, 0x700
	s_lshl_b32 s57, s57, 11
	v_lshl_add_u32 v64, v67, 1, v64
	v_bfe_i32 v67, v65, 6, 1
	s_or_b32 s62, s62, s63
	s_and_b32 s57, s57, 0x1fc000
	s_lshl_b32 s89, s14, 11
	v_and_b32_e32 v67, s14, v67
	v_lshrrev_b32_e32 v65, 7, v65
	v_and_b32_e32 v66, 0x3f0, v66
	v_add_lshl_u32 v65, v67, v65, 10
	s_add_u32 s92, s65, s57
	v_bitop3_b32 v164, v65, v66, v68 bitop3:0xf6
	s_addc_u32 s93, s66, 0
	v_readfirstlane_b32 s57, v189
	s_mov_b32 s63, s15
	v_lshl_add_u64 v[66:67], s[92:93], 0, v[164:165]
	s_mov_b32 m0, s57
	v_readfirstlane_b32 s57, v188
	s_lshl_b64 s[94:95], s[62:63], 13
	v_lshl_add_u64 v[68:69], v[66:67], 0, s[2:3]
	s_mov_b32 m0, s57
	s_add_u32 s94, s40, s94
	v_readfirstlane_b32 s57, v169
	s_addc_u32 s95, s41, s95
	v_mov_b32_e32 v65, v165
	s_mov_b32 m0, s57
	v_lshl_add_u64 v[68:69], s[94:95], 0, v[64:65]
	v_readfirstlane_b32 s57, v187
	s_add_u32 s94, s92, 0x2000
	v_lshl_add_u64 v[70:71], v[68:69], 0, s[4:5]
	s_mov_b32 m0, s57
	s_addc_u32 s95, s93, 0
	v_readfirstlane_b32 s57, v186
	s_bitset1_b32 s62, 7
	s_mov_b32 m0, s57
	v_readfirstlane_b32 s57, v185
	s_lshl_b64 s[62:63], s[62:63], 13
	v_lshl_add_u64 v[66:67], v[66:67], 0, s[8:9]
	s_mov_b32 m0, s57
	s_add_u32 s62, s40, s62
	v_readfirstlane_b32 s57, v184
	s_addc_u32 s63, s41, s63
	s_mov_b32 m0, s57
	v_lshl_add_u64 v[66:67], s[62:63], 0, v[64:65]
	v_readfirstlane_b32 s57, v183
	s_add_u32 s62, s92, s89
	v_lshl_add_u64 v[64:65], v[66:67], 0, s[4:5]
	s_mov_b32 m0, s57
	s_addc_u32 s63, s93, 0
	v_readfirstlane_b32 s57, v182
	v_lshl_add_u64 v[64:65], s[62:63], 0, v[164:165]
	s_mov_b32 m0, s57
	v_readfirstlane_b32 s57, v181
	v_lshl_add_u64 v[64:65], v[64:65], 0, s[2:3]
	s_mov_b32 m0, s57
	v_readfirstlane_b32 s57, v177
	v_lshl_add_u64 v[64:65], v[68:69], 0, s[10:11]
	s_mov_b32 m0, s57
	v_readfirstlane_b32 s57, v175
	s_add_u32 s62, s94, s89
	v_lshl_add_u64 v[64:65], v[68:69], 0, s[12:13]
	s_mov_b32 m0, s57
	s_addc_u32 s63, s95, 0
	v_readfirstlane_b32 s57, v173
	v_lshl_add_u64 v[64:65], s[62:63], 0, v[164:165]
	s_mov_b32 m0, s57
	v_readfirstlane_b32 s57, v171
	v_lshl_add_u64 v[64:65], v[64:65], 0, s[2:3]
	s_mov_b32 m0, s57
	s_nop 0

.LBB0_512:
	s_or_b64 exec, exec, s[56:57]
	s_xor_b64 s[46:47], s[46:47], -1
	s_mov_b64 s[56:57], -1
	s_and_b64 vcc, exec, s[46:47]
	s_cbranch_vccz .LBB0_514
	s_waitcnt vmcnt(22)
	s_mov_b64 s[56:57], 0

.LBB0_516:
	s_mov_b64 s[56:57], -1
	s_and_b64 vcc, exec, s[46:47]
	s_barrier
	s_cbranch_vccz .LBB0_518
	s_waitcnt vmcnt(22)
	s_mov_b64 s[56:57], 0

.LBB0_521:
	ds_read_b128 v[140:143], v138
	ds_read_b128 v[144:147], v138 offset:1024
	ds_read_b128 v[148:151], v138 offset:2048
	ds_read_b128 v[152:155], v138 offset:3072
	ds_read_b128 v[156:159], v193
	ds_read_b128 v[160:163], v193 offset:1024
	ds_read_b128 v[194:197], v192
	ds_read_b128 v[198:201], v192 offset:1024
	ds_read_b128 v[202:205], v191
	ds_read_b128 v[206:209], v191 offset:1024
	ds_read_b128 v[210:213], v190
	ds_read_b128 v[214:217], v190 offset:1024
	s_waitcnt lgkmcnt(8)
	s_waitcnt vmcnt(10)
	s_barrier
	s_waitcnt lgkmcnt(0)
	s_waitcnt lgkmcnt(0)
	v_mfma_f32_16x16x32_bf16 v[124:127], v[140:143], v[156:159], v[124:127]
	v_mfma_f32_16x16x32_bf16 v[120:123], v[148:151], v[156:159], v[120:123]
	v_mfma_f32_16x16x32_bf16 v[116:119], v[140:143], v[194:197], v[116:119]
	v_mfma_f32_16x16x32_bf16 v[112:115], v[148:151], v[194:197], v[112:115]
	v_mfma_f32_16x16x32_bf16 v[108:111], v[140:143], v[202:205], v[108:111]
	v_mfma_f32_16x16x32_bf16 v[104:107], v[148:151], v[202:205], v[104:107]
	v_mfma_f32_16x16x32_bf16 v[100:103], v[140:143], v[210:213], v[100:103]
	v_mfma_f32_16x16x32_bf16 v[96:99], v[148:151], v[210:213], v[96:99]
	v_mfma_f32_16x16x32_bf16 v[124:127], v[144:147], v[160:163], v[124:127]
	v_mfma_f32_16x16x32_bf16 v[120:123], v[152:155], v[160:163], v[120:123]
	v_mfma_f32_16x16x32_bf16 v[116:119], v[144:147], v[198:201], v[116:119]
	v_mfma_f32_16x16x32_bf16 v[112:115], v[152:155], v[198:201], v[112:115]
	v_mfma_f32_16x16x32_bf16 v[108:111], v[144:147], v[206:209], v[108:111]
	v_mfma_f32_16x16x32_bf16 v[104:107], v[152:155], v[206:209], v[104:107]
	v_mfma_f32_16x16x32_bf16 v[100:103], v[144:147], v[214:217], v[100:103]
	v_mfma_f32_16x16x32_bf16 v[96:99], v[152:155], v[214:217], v[96:99]
	s_barrier
	s_add_i32 s36, s98, 0x10000
	v_lshl_add_u64 v[234:235], s[58:59], 0, v[164:165]
	s_mov_b32 m0, s36
	s_add_i32 s36, s98, 0x12000
	ds_read_b128 v[218:221], v135
	ds_read_b128 v[222:225], v135 offset:1024
	ds_read_b128 v[226:229], v135 offset:2048
	ds_read_b128 v[230:233], v135 offset:3072
	global_load_lds_dwordx4 v[234:235], off
	v_lshl_add_u64 v[236:237], v[234:235], 0, s[2:3]
	s_mov_b32 m0, s36
	s_nop 0
	global_load_lds_dwordx4 v[236:237], off
	s_mov_b32 s36, s98
	v_lshl_add_u64 v[236:237], v[128:129], 0, s[22:23]
	s_mov_b32 m0, s36
	s_add_i32 s36, s98, 0x2000
	global_load_lds_dwordx4 v[236:237], off
	v_lshl_add_u64 v[236:237], v[128:129], 0, s[24:25]
	s_mov_b32 m0, s36
	s_nop 0
	global_load_lds_dwordx4 v[236:237], off
	s_waitcnt vmcnt(12)
	s_barrier
	s_waitcnt lgkmcnt(0)
	s_waitcnt lgkmcnt(0)
	v_mfma_f32_16x16x32_bf16 v[92:95], v[218:221], v[156:159], v[92:95]
	v_mfma_f32_16x16x32_bf16 v[88:91], v[226:229], v[156:159], v[88:91]
	v_mfma_f32_16x16x32_bf16 v[84:87], v[218:221], v[194:197], v[84:87]
	v_mfma_f32_16x16x32_bf16 v[80:83], v[226:229], v[194:197], v[80:83]
	v_mfma_f32_16x16x32_bf16 v[76:79], v[218:221], v[202:205], v[76:79]
	v_mfma_f32_16x16x32_bf16 v[72:75], v[226:229], v[202:205], v[72:75]
	v_mfma_f32_16x16x32_bf16 v[68:71], v[218:221], v[210:213], v[68:71]
	v_mfma_f32_16x16x32_bf16 v[64:67], v[226:229], v[210:213], v[64:67]
	v_mfma_f32_16x16x32_bf16 v[92:95], v[222:225], v[160:163], v[92:95]
	v_mfma_f32_16x16x32_bf16 v[88:91], v[230:233], v[160:163], v[88:91]
	v_mfma_f32_16x16x32_bf16 v[84:87], v[222:225], v[198:201], v[84:87]
	v_mfma_f32_16x16x32_bf16 v[80:83], v[230:233], v[198:201], v[80:83]
	v_mfma_f32_16x16x32_bf16 v[76:79], v[222:225], v[206:209], v[76:79]
	v_mfma_f32_16x16x32_bf16 v[72:75], v[230:233], v[206:209], v[72:75]
	v_mfma_f32_16x16x32_bf16 v[68:71], v[222:225], v[214:217], v[68:71]
	v_mfma_f32_16x16x32_bf16 v[64:67], v[230:233], v[214:217], v[64:67]
	s_barrier
	ds_read_b128 v[156:159], v193 offset:16384
	ds_read_b128 v[160:163], v193 offset:17408
	ds_read_b128 v[194:197], v192 offset:16384
	ds_read_b128 v[198:201], v192 offset:17408
	ds_read_b128 v[202:205], v191 offset:16384
	ds_read_b128 v[206:209], v191 offset:17408
	ds_read_b128 v[210:213], v190 offset:16384
	ds_read_b128 v[214:217], v190 offset:17408
	s_add_i32 s36, s98, 0x14000
	v_lshl_add_u64 v[236:237], v[234:235], 0, s[6:7]
	s_mov_b32 m0, s36
	s_add_i32 s36, s98, 0x16000
	global_load_lds_dwordx4 v[236:237], off
	v_lshl_add_u64 v[236:237], v[234:235], 0, s[8:9]
	s_mov_b32 m0, s36
	s_nop 0
	global_load_lds_dwordx4 v[236:237], off
	s_barrier
	s_waitcnt lgkmcnt(0)
	s_waitcnt lgkmcnt(0)
	v_mfma_f32_16x16x32_bf16 v[60:63], v[140:143], v[156:159], v[60:63]
	v_mfma_f32_16x16x32_bf16 v[56:59], v[148:151], v[156:159], v[56:59]
	v_mfma_f32_16x16x32_bf16 v[52:55], v[140:143], v[194:197], v[52:55]
	v_mfma_f32_16x16x32_bf16 v[48:51], v[148:151], v[194:197], v[48:51]
	v_mfma_f32_16x16x32_bf16 v[44:47], v[140:143], v[202:205], v[44:47]
	v_mfma_f32_16x16x32_bf16 v[40:43], v[148:151], v[202:205], v[40:43]
	v_mfma_f32_16x16x32_bf16 v[36:39], v[140:143], v[210:213], v[36:39]
	v_mfma_f32_16x16x32_bf16 v[32:35], v[148:151], v[210:213], v[32:35]
	v_mfma_f32_16x16x32_bf16 v[60:63], v[144:147], v[160:163], v[60:63]
	v_mfma_f32_16x16x32_bf16 v[56:59], v[152:155], v[160:163], v[56:59]
	v_mfma_f32_16x16x32_bf16 v[52:55], v[144:147], v[198:201], v[52:55]
	v_mfma_f32_16x16x32_bf16 v[48:51], v[152:155], v[198:201], v[48:51]
	v_mfma_f32_16x16x32_bf16 v[44:47], v[144:147], v[206:209], v[44:47]
	v_mfma_f32_16x16x32_bf16 v[40:43], v[152:155], v[206:209], v[40:43]
	v_mfma_f32_16x16x32_bf16 v[36:39], v[144:147], v[214:217], v[36:39]
	v_mfma_f32_16x16x32_bf16 v[32:35], v[152:155], v[214:217], v[32:35]
	s_barrier
	s_add_i32 s36, s98, 0x4000
	v_lshl_add_u64 v[142:143], v[128:129], 0, s[26:27]
	s_mov_b32 m0, s36
	s_add_i32 s36, s98, 0x6000
	global_load_lds_dwordx4 v[142:143], off
	s_mov_b32 m0, s36
	s_nop 0
	global_load_lds_dwordx4 v[128:129], off
	s_waitcnt vmcnt(12)
	s_barrier
	v_mfma_f32_16x16x32_bf16 v[28:31], v[218:221], v[156:159], v[28:31]
	v_mfma_f32_16x16x32_bf16 v[24:27], v[226:229], v[156:159], v[24:27]
	v_mfma_f32_16x16x32_bf16 v[20:23], v[218:221], v[194:197], v[20:23]
	v_mfma_f32_16x16x32_bf16 v[16:19], v[226:229], v[194:197], v[16:19]
	v_mfma_f32_16x16x32_bf16 v[12:15], v[218:221], v[202:205], v[12:15]
	v_mfma_f32_16x16x32_bf16 v[8:11], v[226:229], v[202:205], v[8:11]
	v_mfma_f32_16x16x32_bf16 v[4:7], v[218:221], v[210:213], v[4:7]
	v_mfma_f32_16x16x32_bf16 v[0:3], v[226:229], v[210:213], v[0:3]
	v_mfma_f32_16x16x32_bf16 v[28:31], v[222:225], v[160:163], v[28:31]
	v_mfma_f32_16x16x32_bf16 v[24:27], v[230:233], v[160:163], v[24:27]
	v_mfma_f32_16x16x32_bf16 v[20:23], v[222:225], v[198:201], v[20:23]
	v_mfma_f32_16x16x32_bf16 v[16:19], v[230:233], v[198:201], v[16:19]
	v_mfma_f32_16x16x32_bf16 v[12:15], v[222:225], v[206:209], v[12:15]
	v_mfma_f32_16x16x32_bf16 v[8:11], v[230:233], v[206:209], v[8:11]
	v_mfma_f32_16x16x32_bf16 v[4:7], v[222:225], v[214:217], v[4:7]
	v_mfma_f32_16x16x32_bf16 v[0:3], v[230:233], v[214:217], v[0:3]
	s_barrier
	ds_read_b128 v[140:143], v130
	ds_read_b128 v[144:147], v130 offset:1024
	ds_read_b128 v[148:151], v130 offset:2048
	ds_read_b128 v[152:155], v130 offset:3072
	ds_read_b128 v[156:159], v193 offset:32768
	ds_read_b128 v[160:163], v193 offset:33792
	ds_read_b128 v[194:197], v192 offset:32768
	ds_read_b128 v[198:201], v192 offset:33792
	ds_read_b128 v[202:205], v191 offset:32768
	ds_read_b128 v[206:209], v191 offset:33792
	ds_read_b128 v[210:213], v190 offset:32768
	ds_read_b128 v[214:217], v190 offset:33792
	s_waitcnt lgkmcnt(8)
	s_waitcnt vmcnt(10)
	s_barrier
	s_waitcnt lgkmcnt(0)
	s_waitcnt lgkmcnt(0)
	v_mfma_f32_16x16x32_bf16 v[124:127], v[140:143], v[156:159], v[124:127]
	v_mfma_f32_16x16x32_bf16 v[120:123], v[148:151], v[156:159], v[120:123]
	v_mfma_f32_16x16x32_bf16 v[116:119], v[140:143], v[194:197], v[116:119]
	v_mfma_f32_16x16x32_bf16 v[112:115], v[148:151], v[194:197], v[112:115]
	v_mfma_f32_16x16x32_bf16 v[108:111], v[140:143], v[202:205], v[108:111]
	v_mfma_f32_16x16x32_bf16 v[104:107], v[148:151], v[202:205], v[104:107]
	v_mfma_f32_16x16x32_bf16 v[100:103], v[140:143], v[210:213], v[100:103]
	v_mfma_f32_16x16x32_bf16 v[96:99], v[148:151], v[210:213], v[96:99]
	v_mfma_f32_16x16x32_bf16 v[124:127], v[144:147], v[160:163], v[124:127]
	v_mfma_f32_16x16x32_bf16 v[120:123], v[152:155], v[160:163], v[120:123]
	v_mfma_f32_16x16x32_bf16 v[116:119], v[144:147], v[198:201], v[116:119]
	v_mfma_f32_16x16x32_bf16 v[112:115], v[152:155], v[198:201], v[112:115]
	v_mfma_f32_16x16x32_bf16 v[108:111], v[144:147], v[206:209], v[108:111]
	v_mfma_f32_16x16x32_bf16 v[104:107], v[152:155], v[206:209], v[104:107]
	v_mfma_f32_16x16x32_bf16 v[100:103], v[144:147], v[214:217], v[100:103]
	v_mfma_f32_16x16x32_bf16 v[96:99], v[152:155], v[214:217], v[96:99]
	s_barrier
	s_add_i32 s36, s98, 0x18000
	v_lshl_add_u64 v[234:235], s[46:47], 0, v[164:165]
	s_mov_b32 m0, s36
	s_add_i32 s36, s98, 0x1a000
	ds_read_b128 v[218:221], v132
	ds_read_b128 v[222:225], v132 offset:1024
	ds_read_b128 v[226:229], v132 offset:2048
	ds_read_b128 v[230:233], v132 offset:3072
	global_load_lds_dwordx4 v[234:235], off
	v_lshl_add_u64 v[236:237], v[234:235], 0, s[2:3]
	s_mov_b32 m0, s36
	s_nop 0
	global_load_lds_dwordx4 v[236:237], off
	s_add_i32 s36, s98, 0x8000
	v_lshl_add_u64 v[236:237], v[128:129], 0, s[28:29]
	s_mov_b32 m0, s36
	s_add_i32 s36, s98, 0xa000
	global_load_lds_dwordx4 v[236:237], off
	v_lshl_add_u64 v[236:237], v[128:129], 0, s[30:31]
	s_mov_b32 m0, s36
	s_nop 0
	global_load_lds_dwordx4 v[236:237], off
	s_waitcnt vmcnt(12)
	s_barrier
	s_waitcnt lgkmcnt(0)
	s_waitcnt lgkmcnt(0)
	v_mfma_f32_16x16x32_bf16 v[92:95], v[218:221], v[156:159], v[92:95]
	v_mfma_f32_16x16x32_bf16 v[88:91], v[226:229], v[156:159], v[88:91]
	v_mfma_f32_16x16x32_bf16 v[84:87], v[218:221], v[194:197], v[84:87]
	v_mfma_f32_16x16x32_bf16 v[80:83], v[226:229], v[194:197], v[80:83]
	v_mfma_f32_16x16x32_bf16 v[76:79], v[218:221], v[202:205], v[76:79]
	v_mfma_f32_16x16x32_bf16 v[72:75], v[226:229], v[202:205], v[72:75]
	v_mfma_f32_16x16x32_bf16 v[68:71], v[218:221], v[210:213], v[68:71]
	v_mfma_f32_16x16x32_bf16 v[64:67], v[226:229], v[210:213], v[64:67]
	v_mfma_f32_16x16x32_bf16 v[92:95], v[222:225], v[160:163], v[92:95]
	v_mfma_f32_16x16x32_bf16 v[88:91], v[230:233], v[160:163], v[88:91]
	v_mfma_f32_16x16x32_bf16 v[84:87], v[222:225], v[198:201], v[84:87]
	v_mfma_f32_16x16x32_bf16 v[80:83], v[230:233], v[198:201], v[80:83]
	v_mfma_f32_16x16x32_bf16 v[76:79], v[222:225], v[206:209], v[76:79]
	v_mfma_f32_16x16x32_bf16 v[72:75], v[230:233], v[206:209], v[72:75]
	v_mfma_f32_16x16x32_bf16 v[68:71], v[222:225], v[214:217], v[68:71]
	v_mfma_f32_16x16x32_bf16 v[64:67], v[230:233], v[214:217], v[64:67]
	s_barrier
	ds_read_b128 v[156:159], v193 offset:49152
	ds_read_b128 v[160:163], v193 offset:50176
	ds_read_b128 v[194:197], v192 offset:49152
	ds_read_b128 v[198:201], v192 offset:50176
	ds_read_b128 v[202:205], v191 offset:49152
	ds_read_b128 v[206:209], v191 offset:50176
	ds_read_b128 v[210:213], v190 offset:49152
	ds_read_b128 v[214:217], v190 offset:50176
	s_add_i32 s36, s98, 0x1c000
	v_lshl_add_u64 v[236:237], v[234:235], 0, s[6:7]
	s_mov_b32 m0, s36
	s_add_i32 s36, s98, 0x1e000
	global_load_lds_dwordx4 v[236:237], off
	v_lshl_add_u64 v[236:237], v[234:235], 0, s[8:9]
	s_mov_b32 m0, s36
	s_nop 0
	global_load_lds_dwordx4 v[236:237], off
	s_barrier
	s_waitcnt lgkmcnt(0)
	s_waitcnt lgkmcnt(0)
	v_mfma_f32_16x16x32_bf16 v[60:63], v[140:143], v[156:159], v[60:63]
	v_mfma_f32_16x16x32_bf16 v[56:59], v[148:151], v[156:159], v[56:59]
	v_mfma_f32_16x16x32_bf16 v[52:55], v[140:143], v[194:197], v[52:55]
	v_mfma_f32_16x16x32_bf16 v[48:51], v[148:151], v[194:197], v[48:51]
	v_mfma_f32_16x16x32_bf16 v[44:47], v[140:143], v[202:205], v[44:47]
	v_mfma_f32_16x16x32_bf16 v[40:43], v[148:151], v[202:205], v[40:43]
	v_mfma_f32_16x16x32_bf16 v[36:39], v[140:143], v[210:213], v[36:39]
	v_mfma_f32_16x16x32_bf16 v[32:35], v[148:151], v[210:213], v[32:35]
	v_mfma_f32_16x16x32_bf16 v[60:63], v[144:147], v[160:163], v[60:63]
	v_mfma_f32_16x16x32_bf16 v[56:59], v[152:155], v[160:163], v[56:59]
	v_mfma_f32_16x16x32_bf16 v[52:55], v[144:147], v[198:201], v[52:55]
	v_mfma_f32_16x16x32_bf16 v[48:51], v[152:155], v[198:201], v[48:51]
	v_mfma_f32_16x16x32_bf16 v[44:47], v[144:147], v[206:209], v[44:47]
	v_mfma_f32_16x16x32_bf16 v[40:43], v[152:155], v[206:209], v[40:43]
	v_mfma_f32_16x16x32_bf16 v[36:39], v[144:147], v[214:217], v[36:39]
	v_mfma_f32_16x16x32_bf16 v[32:35], v[152:155], v[214:217], v[32:35]
	s_barrier
	v_lshl_add_u64 v[128:129], v[128:129], 0, s[34:35]
	s_add_i32 s36, s98, 0xc000
	v_lshl_add_u64 v[142:143], v[128:129], 0, s[18:19]
	s_mov_b32 m0, s36
	s_add_i32 s36, s98, 0xe000
	global_load_lds_dwordx4 v[142:143], off
	v_lshl_add_u64 v[142:143], v[128:129], 0, s[20:21]
	s_mov_b32 m0, s36
	s_nop 0
	global_load_lds_dwordx4 v[142:143], off
	s_waitcnt vmcnt(12)
	s_barrier
	v_mfma_f32_16x16x32_bf16 v[28:31], v[218:221], v[156:159], v[28:31]
	v_mfma_f32_16x16x32_bf16 v[24:27], v[226:229], v[156:159], v[24:27]
	v_mfma_f32_16x16x32_bf16 v[20:23], v[218:221], v[194:197], v[20:23]
	v_mfma_f32_16x16x32_bf16 v[16:19], v[226:229], v[194:197], v[16:19]
	v_mfma_f32_16x16x32_bf16 v[12:15], v[218:221], v[202:205], v[12:15]
	v_mfma_f32_16x16x32_bf16 v[8:11], v[226:229], v[202:205], v[8:11]
	v_mfma_f32_16x16x32_bf16 v[4:7], v[218:221], v[210:213], v[4:7]
	v_mfma_f32_16x16x32_bf16 v[0:3], v[226:229], v[210:213], v[0:3]
	v_mfma_f32_16x16x32_bf16 v[28:31], v[222:225], v[160:163], v[28:31]
	v_mfma_f32_16x16x32_bf16 v[24:27], v[230:233], v[160:163], v[24:27]
	v_mfma_f32_16x16x32_bf16 v[20:23], v[222:225], v[198:201], v[20:23]
	v_mfma_f32_16x16x32_bf16 v[16:19], v[230:233], v[198:201], v[16:19]
	v_mfma_f32_16x16x32_bf16 v[12:15], v[222:225], v[206:209], v[12:15]
	v_mfma_f32_16x16x32_bf16 v[8:11], v[230:233], v[206:209], v[8:11]
	v_mfma_f32_16x16x32_bf16 v[4:7], v[222:225], v[214:217], v[4:7]
	v_mfma_f32_16x16x32_bf16 v[0:3], v[230:233], v[214:217], v[0:3]
	s_add_i32 s14, s14, 2
	s_add_u32 s46, s46, s56
	s_addc_u32 s47, s47, s57
	s_add_u32 s58, s58, s56
	s_addc_u32 s59, s59, s57
	s_cmp_lt_u32 s14, 28
	s_barrier
	s_cbranch_scc1 .LBB0_521
	s_lshl_b32 s14, s60, 3
	s_or_b32 s80, s61, s14
	s_lshl_b32 s46, s80, 8
	v_lshlrev_b32_e32 v128, 3, v131
	v_lshlrev_b32_e32 v129, 5, v131
	s_or_b32 s14, s46, 0x80
	v_and_b32_e32 v128, 0x7fff0, v128
	v_and_b32_e32 v129, 32, v129
	s_lshl_b64 s[56:57], s[14:15], 13
	v_add_u32_e32 v129, v129, v134
	v_add_lshl_u32 v128, v133, v128, 13
	s_add_u32 s56, s40, s56
	v_lshl_add_u32 v164, v129, 1, v128
	s_addc_u32 s57, s41, s57
	v_lshl_add_u64 v[128:129], s[56:57], 0, v[164:165]
	v_readfirstlane_b32 s14, v137
	ds_read_b128 v[140:143], v138
	ds_read_b128 v[144:147], v138 offset:1024
	ds_read_b128 v[148:151], v138 offset:2048
	ds_read_b128 v[152:155], v138 offset:3072
	ds_read_b128 v[156:159], v193
	ds_read_b128 v[160:163], v193 offset:1024
	ds_read_b128 v[194:197], v192
	ds_read_b128 v[198:201], v192 offset:1024
	ds_read_b128 v[202:205], v191
	ds_read_b128 v[206:209], v191 offset:1024
	ds_read_b128 v[210:213], v190
	ds_read_b128 v[214:217], v190 offset:1024
	v_lshl_add_u64 v[138:139], v[128:129], 0, s[38:39]
	s_mov_b32 m0, s14
	v_readfirstlane_b32 s14, v136
	global_load_lds_dwordx4 v[138:139], off
	v_lshl_add_u64 v[128:129], v[128:129], 0, s[44:45]
	s_mov_b32 m0, s14
	s_mov_b32 s47, s15
	global_load_lds_dwordx4 v[128:129], off
	s_mul_i32 s99, s76, s84
	s_add_i32 s99, s99, s33
	s_cmpk_lt_u32 s99, 0x400
	s_cbranch_scc1 .Lxt12_has
	s_mov_b32 s99, 0
	s_branch .Lxt12_set
.Lxt12_has:
	v_mbcnt_lo_u32_b32 v248, -1, 0
	v_mbcnt_hi_u32_b32 v248, -1, v248
	v_add_u32_e32 v249, s64, v248
	v_bfe_i32 v252, v249, 27, 1
	v_lshlrev_b32_e32 v250, 4, v249
	v_lshrrev_b32_e32 v252, 22, v252
	v_add_u32_e32 v252, v250, v252
	v_and_b32_e32 v252, 0xfffffc00, v252
	v_sub_u32_e32 v252, v250, v252
	v_lshrrev_b32_e32 v253, 4, v252
	v_bitop3_b32 v252, v253, v252, 32 bitop3:0x6c
	v_ashrrev_i32_e32 v251, 31, v249
	v_ashrrev_i32_e32 v254, 31, v252
	v_lshrrev_b32_e32 v251, 26, v251
	v_lshrrev_b32_e32 v254, 26, v254
	v_add_u32_e32 v251, v249, v251
	v_add_u32_e32 v254, v252, v254
	v_ashrrev_i32_e32 v251, 6, v251
	v_lshrrev_b32_e32 v255, 6, v254
	v_and_b32_e32 v254, 0xc0, v254
	v_lshlrev_b32_e32 v253, 3, v251
	v_lshlrev_b32_e32 v251, 5, v251
	v_sub_u32_e32 v252, v252, v254
	v_and_b32_e32 v253, 0x7fff0, v253
	v_and_b32_e32 v251, 32, v251
	v_ashrrev_i16_sdwa v252, v167, sext(v252) dst_sel:DWORD dst_unused:UNUSED_PAD src0_sel:DWORD src1_sel:BYTE_0
	s_nop 0
	v_add_u32_sdwa v251, v251, sext(v252) dst_sel:DWORD dst_unused:UNUSED_PAD src0_sel:DWORD src1_sel:WORD_0
	s_nop 0
	v_and_b32_e32 v252, 32, v248
	v_add_lshl_u32 v248, v255, v253, 13
	v_lshl_add_u32 v248, v251, 1, v248
	v_bfe_i32 v251, v249, 6, 1
	v_and_b32_e32 v251, 0x200, v251
	v_lshrrev_b32_e32 v249, 7, v249
	v_and_b32_e32 v250, 0x3f0, v250
	v_add_lshl_u32 v249, v251, v249, 10
	v_bitop3_b32 v243, v249, v250, v252 bitop3:0xf6
	s_lshr_b32 s100, s99, 8
	s_lshl_b32 s100, s100, 11
	s_lshl_b32 s101, s99, 8
	s_and_b32 s101, s101, 0x700
	s_or_b32 s100, s100, s101
	s_lshl_b32 s100, s100, 13
	s_add_u32 s100, s40, s100
	s_addc_u32 s101, s41, 0
	v_mov_b32_e32 v249, 0
	v_lshl_add_u64 v[244:245], s[100:101], 0, v[248:249]
	s_and_b32 s100, s99, 0xf8
	s_lshl_b32 s100, s100, 11
	s_add_u32 s100, s62, s100
	s_addc_u32 s101, s63, 0
	v_mov_b32_e32 v252, v243
	v_mov_b32_e32 v253, 0
	v_lshl_add_u64 v[246:247], s[100:101], 0, v[252:253]
	s_mov_b32 s99, 1

.Lxt12_w3d:
	s_barrier
	s_waitcnt lgkmcnt(0)
	s_setprio 1
	s_waitcnt lgkmcnt(0)
	v_mfma_f32_16x16x32_bf16 v[100:103], v[88:91], v[140:143], v[156:159]
	v_mfma_f32_16x16x32_bf16 v[108:111], v[92:95], v[140:143], v[160:163]
	v_mfma_f32_16x16x32_bf16 v[116:119], v[88:91], v[218:221], v[194:197]
	v_mfma_f32_16x16x32_bf16 v[124:127], v[92:95], v[218:221], v[198:201]
	v_mfma_f32_16x16x32_bf16 v[160:163], v[88:91], v[226:229], v[202:205]
	v_mfma_f32_16x16x32_bf16 v[194:197], v[92:95], v[226:229], v[206:209]
	v_mfma_f32_16x16x32_bf16 v[198:201], v[88:91], v[234:237], v[210:213]
	v_mfma_f32_16x16x32_bf16 v[202:205], v[92:95], v[234:237], v[214:217]
	v_mfma_f32_16x16x32_bf16 v[156:159], v[80:83], v[148:151], v[100:103]
	v_mfma_f32_16x16x32_bf16 v[148:151], v[84:87], v[148:151], v[108:111]
	v_mfma_f32_16x16x32_bf16 v[140:143], v[80:83], v[222:225], v[116:119]
	v_mfma_f32_16x16x32_bf16 v[132:135], v[84:87], v[222:225], v[124:127]
	v_mfma_f32_16x16x32_bf16 v[124:127], v[80:83], v[230:233], v[160:163]
	v_mfma_f32_16x16x32_bf16 v[116:119], v[84:87], v[230:233], v[194:197]
	v_mfma_f32_16x16x32_bf16 v[108:111], v[80:83], v[238:241], v[198:201]
	v_mfma_f32_16x16x32_bf16 v[100:103], v[84:87], v[238:241], v[202:205]
	s_setprio 0
	s_lshl_b64 s[56:57], s[46:47], 2
	s_barrier
	v_mbcnt_lo_u32_b32 v162, -1, 0
	v_mbcnt_hi_u32_b32 v162, -1, v162
	s_add_u32 s56, s87, s56
	v_add_u32_e32 v160, s64, v162
	s_addc_u32 s57, s88, s57
	v_and_b32_e32 v164, 0x100, v160
	v_and_b32_e32 v162, 15, v162
	v_lshl_add_u64 v[160:161], s[56:57], 0, v[164:165]
	v_lshlrev_b32_e32 v164, 2, v162
	v_lshl_add_u64 v[160:161], v[160:161], 0, v[164:165]
	global_load_dword v180, v[160:161], off
	global_load_dword v178, v[160:161], off offset:64
	global_load_dword v176, v[160:161], off offset:128
	global_load_dword v174, v[160:161], off offset:192
	global_load_dword v172, v[160:161], off offset:512
	global_load_dword v170, v[160:161], off offset:576
	global_load_dword v168, v[160:161], off offset:640
	global_load_dword v166, v[160:161], off offset:704
	v_mbcnt_lo_u32_b32 v194, -1, 0
	v_mbcnt_hi_u32_b32 v194, -1, v194
	s_cmp_lg_u32 s79, 0
	v_add_u32_e32 v160, s64, v194
	v_bfe_u32 v196, v160, 8, 1
	v_ashrrev_i32_e32 v199, 6, v160
	v_bfe_u32 v160, v194, 4, 2
	s_cselect_b64 s[56:57], -1, 0
	v_and_b32_e32 v197, 3, v199
	v_and_b32_e32 v195, 15, v194
	s_and_b64 vcc, exec, s[56:57]
	v_lshlrev_b32_e32 v198, 4, v160
	s_cbranch_vccz .LBB0_533
	s_lshl_b32 s14, s78, 22
	s_lshl_b32 s36, s80, 14
	s_add_i32 s36, s36, s14
	v_lshlrev_b32_e32 v160, 6, v195
	v_or3_b32 v160, s36, v160, v198
	v_lshl_add_u32 v160, v197, 20, v160
	v_lshl_or_b32 v164, v196, 12, v160
	s_waitcnt vmcnt(0)
	s_cmp_eq_u32 s99, 0
	s_cbranch_scc1 .Lxt12_s4
	s_mov_b64 s[100:101], 0x100000
	s_add_i32 m0, s98, 0x18000
	v_lshl_add_u64 v[250:251], v[246:247], 0, s[100:101]
	global_load_lds_dwordx4 v[250:251], off
	s_mov_b64 s[100:101], 0x101000
	s_add_i32 m0, s98, 0x1a000
	v_lshl_add_u64 v[250:251], v[246:247], 0, s[100:101]
	global_load_lds_dwordx4 v[250:251], off
	s_mov_b64 s[100:101], 0x80
	s_add_i32 m0, s98, 0x8000
	v_lshl_add_u64 v[250:251], v[244:245], 0, s[100:101]
	global_load_lds_dwordx4 v[250:251], off
	s_mov_b64 s[100:101], 0x80080
	s_add_i32 m0, s98, 0xa000
	v_lshl_add_u64 v[250:251], v[244:245], 0, s[100:101]
	global_load_lds_dwordx4 v[250:251], off
	s_mov_b64 s[100:101], 0x102000
	s_add_i32 m0, s98, 0x1c000
	v_lshl_add_u64 v[250:251], v[246:247], 0, s[100:101]
	global_load_lds_dwordx4 v[250:251], off
	s_mov_b64 s[100:101], 0x103000
	s_add_i32 m0, s98, 0x1e000
	v_lshl_add_u64 v[250:251], v[246:247], 0, s[100:101]
	global_load_lds_dwordx4 v[250:251], off
.Lxt12_s4:
	v_pk_mul_f32 v[160:161], v[154:155], v[180:181] op_sel_hi:[1,0]
	v_pk_mul_f32 v[200:201], v[146:147], v[180:181] op_sel_hi:[1,0]
	v_max_f32_e32 v160, 0, v160
	v_mul_f32_e32 v204, v160, v160
	v_max_f32_e32 v160, 0, v200
	v_pk_mul_f32 v[162:163], v[152:153], v[180:181] op_sel_hi:[1,0]
	v_mul_f32_e32 v200, v160, v160
	v_max_f32_e32 v160, 0, v161
	v_pk_mul_f32 v[202:203], v[144:145], v[180:181] op_sel_hi:[1,0]
	v_max_f32_e32 v162, 0, v162
	v_max_f32_e32 v163, 0, v163
	v_mul_f32_e32 v161, v160, v160
	v_max_f32_e32 v160, 0, v201
	v_mul_f32_e32 v162, v162, v162
	v_max_f32_e32 v202, 0, v202
	v_mul_f32_e32 v163, v163, v163
	v_max_f32_e32 v203, 0, v203
	v_mul_f32_e32 v201, v160, v160
	v_cvt_pk_bf16_f32 v160, v162, v163
	v_cvt_pk_bf16_f32 v161, v204, v161
	v_mul_f32_e32 v202, v202, v202
	v_mul_f32_e32 v203, v203, v203
	v_cvt_pk_bf16_f32 v162, v202, v203
	v_cvt_pk_bf16_f32 v163, v200, v201
	global_store_dwordx4 v164, v[160:163], s[0:1]
	v_pk_mul_f32 v[202:203], v[150:151], v[180:181] op_sel_hi:[1,0]
	v_lshl_add_u64 v[200:201], s[0:1], 0, v[164:165]
	v_pk_mul_f32 v[160:161], v[158:159], v[180:181] op_sel_hi:[1,0]
	v_pk_mul_f32 v[162:163], v[156:157], v[180:181] op_sel_hi:[1,0]
	v_max_f32_e32 v160, 0, v160
	v_mul_f32_e32 v206, v160, v160
	v_max_f32_e32 v160, 0, v202
	v_mul_f32_e32 v202, v160, v160
	v_max_f32_e32 v160, 0, v161
	v_pk_mul_f32 v[204:205], v[148:149], v[180:181] op_sel_hi:[1,0]
	v_max_f32_e32 v162, 0, v162
	v_max_f32_e32 v163, 0, v163
	v_mul_f32_e32 v161, v160, v160
	v_max_f32_e32 v160, 0, v203
	v_add_co_u32_e32 v200, vcc, s72, v200
	v_mul_f32_e32 v162, v162, v162
	v_max_f32_e32 v204, 0, v204
	v_mul_f32_e32 v163, v163, v163
	v_max_f32_e32 v205, 0, v205
	v_mul_f32_e32 v203, v160, v160
	v_cvt_pk_bf16_f32 v160, v162, v163
	v_cvt_pk_bf16_f32 v161, v206, v161
	v_addc_co_u32_e32 v201, vcc, 0, v201, vcc
	v_mul_f32_e32 v204, v204, v204
	v_mul_f32_e32 v205, v205, v205
	v_cvt_pk_bf16_f32 v162, v204, v205
	v_cvt_pk_bf16_f32 v163, v202, v203
	global_store_dwordx4 v[200:201], v[160:163], off
	v_pk_mul_f32 v[202:203], v[130:131], v[178:179] op_sel_hi:[1,0]
	v_pk_mul_f32 v[204:205], v[128:129], v[178:179] op_sel_hi:[1,0]
	v_pk_mul_f32 v[160:161], v[138:139], v[178:179] op_sel_hi:[1,0]
	v_pk_mul_f32 v[162:163], v[136:137], v[178:179] op_sel_hi:[1,0]
	v_max_f32_e32 v160, 0, v160
	v_mul_f32_e32 v206, v160, v160
	v_max_f32_e32 v160, 0, v202
	v_mul_f32_e32 v202, v160, v160
	v_max_f32_e32 v160, 0, v161
	v_max_f32_e32 v162, 0, v162
	v_max_f32_e32 v163, 0, v163
	v_mul_f32_e32 v161, v160, v160
	v_max_f32_e32 v160, 0, v203
	v_mul_f32_e32 v162, v162, v162
	v_max_f32_e32 v204, 0, v204
	v_mul_f32_e32 v163, v163, v163
	v_max_f32_e32 v205, 0, v205
	v_mul_f32_e32 v203, v160, v160
	v_cvt_pk_bf16_f32 v160, v162, v163
	v_cvt_pk_bf16_f32 v161, v206, v161
	v_mul_f32_e32 v204, v204, v204
	v_mul_f32_e32 v205, v205, v205
	v_cvt_pk_bf16_f32 v162, v204, v205
	v_cvt_pk_bf16_f32 v163, v202, v203
	global_store_dwordx4 v164, v[160:163], s[0:1] offset:1024
	v_pk_mul_f32 v[202:203], v[134:135], v[178:179] op_sel_hi:[1,0]
	v_pk_mul_f32 v[204:205], v[132:133], v[178:179] op_sel_hi:[1,0]
	v_pk_mul_f32 v[160:161], v[142:143], v[178:179] op_sel_hi:[1,0]
	v_pk_mul_f32 v[162:163], v[140:141], v[178:179] op_sel_hi:[1,0]
	v_max_f32_e32 v160, 0, v160
	v_mul_f32_e32 v206, v160, v160
	v_max_f32_e32 v160, 0, v202
	v_mul_f32_e32 v202, v160, v160
	v_max_f32_e32 v160, 0, v161
	v_max_f32_e32 v162, 0, v162
	v_max_f32_e32 v163, 0, v163
	v_mul_f32_e32 v161, v160, v160
	v_max_f32_e32 v160, 0, v203
	v_mul_f32_e32 v162, v162, v162
	v_max_f32_e32 v204, 0, v204
	v_mul_f32_e32 v163, v163, v163
	v_max_f32_e32 v205, 0, v205
	v_mul_f32_e32 v203, v160, v160
	v_cvt_pk_bf16_f32 v160, v162, v163
	v_cvt_pk_bf16_f32 v161, v206, v161
	v_mul_f32_e32 v204, v204, v204
	v_mul_f32_e32 v205, v205, v205
	v_cvt_pk_bf16_f32 v162, v204, v205
	v_cvt_pk_bf16_f32 v163, v202, v203
	global_store_dwordx4 v[200:201], v[160:163], off offset:1024
	v_pk_mul_f32 v[202:203], v[114:115], v[176:177] op_sel_hi:[1,0]
	v_pk_mul_f32 v[204:205], v[112:113], v[176:177] op_sel_hi:[1,0]
	v_pk_mul_f32 v[160:161], v[122:123], v[176:177] op_sel_hi:[1,0]
	v_pk_mul_f32 v[162:163], v[120:121], v[176:177] op_sel_hi:[1,0]
	v_max_f32_e32 v160, 0, v160
	v_mul_f32_e32 v206, v160, v160
	v_max_f32_e32 v160, 0, v202
	v_mul_f32_e32 v202, v160, v160
	v_max_f32_e32 v160, 0, v161
	v_max_f32_e32 v162, 0, v162
	v_max_f32_e32 v163, 0, v163
	v_mul_f32_e32 v161, v160, v160
	v_max_f32_e32 v160, 0, v203
	v_mul_f32_e32 v162, v162, v162
	v_max_f32_e32 v204, 0, v204
	v_mul_f32_e32 v163, v163, v163
	v_max_f32_e32 v205, 0, v205
	v_mul_f32_e32 v203, v160, v160
	v_cvt_pk_bf16_f32 v160, v162, v163
	v_cvt_pk_bf16_f32 v161, v206, v161
	v_mul_f32_e32 v204, v204, v204
	v_mul_f32_e32 v205, v205, v205
	v_cvt_pk_bf16_f32 v162, v204, v205
	v_cvt_pk_bf16_f32 v163, v202, v203
	global_store_dwordx4 v164, v[160:163], s[0:1] offset:2048
	v_pk_mul_f32 v[202:203], v[118:119], v[176:177] op_sel_hi:[1,0]
	v_pk_mul_f32 v[204:205], v[116:117], v[176:177] op_sel_hi:[1,0]
	v_pk_mul_f32 v[160:161], v[126:127], v[176:177] op_sel_hi:[1,0]
	v_pk_mul_f32 v[162:163], v[124:125], v[176:177] op_sel_hi:[1,0]
	v_max_f32_e32 v160, 0, v160
	v_mul_f32_e32 v206, v160, v160
	v_max_f32_e32 v160, 0, v202
	v_mul_f32_e32 v202, v160, v160
	v_max_f32_e32 v160, 0, v161
	v_max_f32_e32 v162, 0, v162
	v_max_f32_e32 v163, 0, v163
	v_mul_f32_e32 v161, v160, v160
	v_max_f32_e32 v160, 0, v203
	v_mul_f32_e32 v162, v162, v162
	v_max_f32_e32 v204, 0, v204
	v_mul_f32_e32 v163, v163, v163
	v_max_f32_e32 v205, 0, v205
	v_mul_f32_e32 v203, v160, v160
	v_cvt_pk_bf16_f32 v160, v162, v163
	v_cvt_pk_bf16_f32 v161, v206, v161
	v_mul_f32_e32 v204, v204, v204
	v_mul_f32_e32 v205, v205, v205
	v_cvt_pk_bf16_f32 v162, v204, v205
	v_cvt_pk_bf16_f32 v163, v202, v203
	global_store_dwordx4 v[200:201], v[160:163], off offset:2048
	v_pk_mul_f32 v[200:201], v[98:99], v[174:175] op_sel_hi:[1,0]
	v_pk_mul_f32 v[202:203], v[96:97], v[174:175] op_sel_hi:[1,0]
	v_pk_mul_f32 v[160:161], v[106:107], v[174:175] op_sel_hi:[1,0]
	v_pk_mul_f32 v[162:163], v[104:105], v[174:175] op_sel_hi:[1,0]
	v_max_f32_e32 v160, 0, v160
	v_mul_f32_e32 v204, v160, v160
	v_max_f32_e32 v160, 0, v200
	v_mul_f32_e32 v200, v160, v160
	v_max_f32_e32 v160, 0, v161
	v_max_f32_e32 v162, 0, v162
	v_max_f32_e32 v163, 0, v163
	v_mul_f32_e32 v161, v160, v160
	v_max_f32_e32 v160, 0, v201
	v_mul_f32_e32 v162, v162, v162
	v_max_f32_e32 v202, 0, v202
	v_mul_f32_e32 v163, v163, v163
	v_max_f32_e32 v203, 0, v203
	v_mul_f32_e32 v201, v160, v160
	v_cvt_pk_bf16_f32 v160, v162, v163
	v_cvt_pk_bf16_f32 v161, v204, v161
	v_mul_f32_e32 v202, v202, v202
	v_mul_f32_e32 v203, v203, v203
	v_cvt_pk_bf16_f32 v162, v202, v203
	v_cvt_pk_bf16_f32 v163, v200, v201
	global_store_dwordx4 v164, v[160:163], s[0:1] offset:3072
	v_pk_mul_f32 v[200:201], v[102:103], v[174:175] op_sel_hi:[1,0]
	v_pk_mul_f32 v[202:203], v[100:101], v[174:175] op_sel_hi:[1,0]
	v_pk_mul_f32 v[160:161], v[110:111], v[174:175] op_sel_hi:[1,0]
	v_pk_mul_f32 v[162:163], v[108:109], v[174:175] op_sel_hi:[1,0]
	v_max_f32_e32 v160, 0, v160
	v_mul_f32_e32 v204, v160, v160
	v_max_f32_e32 v160, 0, v200
	v_max_f32_e32 v162, 0, v162
	v_max_f32_e32 v163, 0, v163
	v_mul_f32_e32 v200, v160, v160
	v_max_f32_e32 v160, 0, v161
	v_mul_f32_e32 v162, v162, v162
	v_max_f32_e32 v202, 0, v202
	v_mul_f32_e32 v163, v163, v163
	v_max_f32_e32 v203, 0, v203
	v_mul_f32_e32 v161, v160, v160
	v_max_f32_e32 v160, 0, v201
	v_mul_f32_e32 v202, v202, v202
	v_mul_f32_e32 v203, v203, v203
	v_mul_f32_e32 v201, v160, v160
	v_cvt_pk_bf16_f32 v160, v162, v163
	v_cvt_pk_bf16_f32 v161, v204, v161
	v_cvt_pk_bf16_f32 v162, v202, v203
	v_cvt_pk_bf16_f32 v163, v200, v201
	v_add_u32_e32 v164, 0x80c00, v164
	s_cbranch_execnz .LBB0_525

.LBB0_530:
	v_mbcnt_lo_u32_b32 v64, -1, 0
	v_mbcnt_hi_u32_b32 v64, -1, v64
	s_lshl_b32 s36, s81, 3
	v_add_u32_e32 v65, s64, v64
	v_bfe_i32 v68, v65, 27, 1
	v_lshlrev_b32_e32 v66, 4, v65
	v_lshrrev_b32_e32 v68, 22, v68
	v_add_u32_e32 v68, v66, v68
	v_and_b32_e32 v68, 0xfffffc00, v68
	v_sub_u32_e32 v68, v66, v68
	v_lshrrev_b32_e32 v69, 4, v68
	v_bitop3_b32 v68, v69, v68, 32 bitop3:0x6c
	v_ashrrev_i32_e32 v67, 31, v65
	v_ashrrev_i32_e32 v70, 31, v68
	v_lshrrev_b32_e32 v67, 26, v67
	v_lshrrev_b32_e32 v70, 26, v70
	v_add_u32_e32 v67, v65, v67
	v_add_u32_e32 v70, v68, v70
	v_ashrrev_i32_e32 v67, 6, v67
	v_lshrrev_b32_e32 v71, 6, v70
	v_and_b32_e32 v70, 0xc0, v70
	v_lshlrev_b32_e32 v69, 3, v67
	v_lshlrev_b32_e32 v67, 5, v67
	v_sub_u32_e32 v68, v68, v70
	s_ff1_i32_b32 s37, s36
	s_add_i32 s36, s36, -1
	v_and_b32_e32 v69, 0x7fff0, v69
	v_and_b32_e32 v67, 32, v67
	v_ashrrev_i16_sdwa v68, v167, sext(v68) dst_sel:DWORD dst_unused:UNUSED_PAD src0_sel:DWORD src1_sel:BYTE_0
	s_lshr_b32 s37, s82, s37
	s_and_b32 s36, s36, s82
	s_lshl_b32 s47, s82, 8
	v_add_u32_sdwa v67, v67, sext(v68) dst_sel:DWORD dst_unused:UNUSED_PAD src0_sel:DWORD src1_sel:WORD_0
	v_and_b32_e32 v68, 32, v64
	v_add_lshl_u32 v64, v71, v69, 13
	s_lshl_b32 s37, s37, 11
	s_and_b32 s47, s47, 0x700
	s_lshl_b32 s36, s36, 11
	v_lshl_add_u32 v64, v67, 1, v64
	v_bfe_i32 v67, v65, 6, 1
	s_or_b32 s60, s37, s47
	s_and_b32 s36, s36, 0x1fc000
	s_lshl_b32 s37, s14, 11
	v_and_b32_e32 v67, s14, v67
	v_lshrrev_b32_e32 v65, 7, v65
	v_and_b32_e32 v66, 0x3f0, v66
	v_add_lshl_u32 v65, v67, v65, 10
	s_add_u32 s90, s62, s36
	v_bitop3_b32 v164, v65, v66, v68 bitop3:0xf6
	s_addc_u32 s91, s63, 0
	v_readfirstlane_b32 s36, v189
	s_mov_b32 s61, s15
	v_lshl_add_u64 v[66:67], s[90:91], 0, v[164:165]
	s_mov_b32 m0, s36
	v_readfirstlane_b32 s36, v188
	s_lshl_b64 s[92:93], s[60:61], 13
	v_lshl_add_u64 v[68:69], v[66:67], 0, s[2:3]
	s_mov_b32 m0, s36
	s_add_u32 s92, s40, s92
	v_readfirstlane_b32 s36, v169
	s_addc_u32 s93, s41, s93
	v_mov_b32_e32 v65, v165
	s_mov_b32 m0, s36
	v_lshl_add_u64 v[68:69], s[92:93], 0, v[64:65]
	v_readfirstlane_b32 s36, v187
	s_add_u32 s92, s90, 0x2000
	v_lshl_add_u64 v[70:71], v[68:69], 0, s[4:5]
	s_mov_b32 m0, s36
	s_addc_u32 s93, s91, 0
	v_readfirstlane_b32 s36, v186
	s_bitset1_b32 s60, 7
	s_mov_b32 m0, s36
	v_readfirstlane_b32 s36, v185
	s_lshl_b64 s[60:61], s[60:61], 13
	v_lshl_add_u64 v[66:67], v[66:67], 0, s[8:9]
	s_mov_b32 m0, s36
	s_add_u32 s60, s40, s60
	v_readfirstlane_b32 s36, v184
	s_addc_u32 s61, s41, s61
	s_mov_b32 m0, s36
	v_lshl_add_u64 v[66:67], s[60:61], 0, v[64:65]
	v_readfirstlane_b32 s36, v183
	s_add_u32 s60, s90, s37
	v_lshl_add_u64 v[64:65], v[66:67], 0, s[4:5]
	s_mov_b32 m0, s36
	s_addc_u32 s61, s91, 0
	v_readfirstlane_b32 s36, v182
	v_lshl_add_u64 v[64:65], s[60:61], 0, v[164:165]
	s_mov_b32 m0, s36
	v_readfirstlane_b32 s36, v181
	v_lshl_add_u64 v[64:65], v[64:65], 0, s[2:3]
	s_mov_b32 m0, s36
	v_readfirstlane_b32 s36, v177
	v_lshl_add_u64 v[64:65], v[68:69], 0, s[10:11]
	s_mov_b32 m0, s36
	v_readfirstlane_b32 s36, v175
	s_add_u32 s60, s92, s37
	v_lshl_add_u64 v[64:65], v[68:69], 0, s[12:13]
	s_mov_b32 m0, s36
	s_addc_u32 s61, s93, 0
	v_readfirstlane_b32 s36, v173
	v_lshl_add_u64 v[64:65], s[60:61], 0, v[164:165]
	s_mov_b32 m0, s36
	v_readfirstlane_b32 s36, v171
	v_lshl_add_u64 v[64:65], v[64:65], 0, s[2:3]
	s_mov_b32 m0, s36
	s_nop 0
